# final: hand-rewritten gathered attention (16-key blocks, K prefetch, DPP reductions, per-query and per-block workgroup barriers for L2 locality), batched weight-transpose loads, EpiRes epilogue load h
# speedup vs baseline: 1.0424x; 1.0424x over previous
; __device__ __forceinline__ void unpack8(u32x4 w, float* v) { v[0] = bflo(w.x); v[1] = bfhi(w.x); v[2] = bflo(w.y); v[3] = bfhi(w.y); v[4] = bflo(w.z); v[5] = bfhi(w.z); v[6] = bflo(w.w); v[7] = bfhi(w.w); }
; __device__ __forceinline__ void attn_phase(const Args& a, unsigned char* lds, int lane, int wave) {
;     ...
;     for (int t = gw; t < TT; t += NGW) {
;         const bool sample = t >= TP; const int bb = sample ? (t - TP) >> 6 : 0;
;         const int c = t >> 6; const int L = sample ? 1088 : 64 * (c + 1);
;         const int nsel = min(256, L);
;         const unsigned* cand = CAND + (size_t)t * 256;
; #pragma unroll
;         for (int j = 0; j < 4; ++j) { const int i = j * 64 + lane; if (i < nsel) sel[i] = cand[i] & 0x3FFFu; }
;         bf16_t* qp = P + (size_t)t * NP + lane * 16;
;         float q[16]; unpack8(*(const u32x4*)qp, q); unpack8(*(const u32x4*)(qp + 8), q + 8);
.Lat_q:
	s_barrier
	s_and_b32 s0, s2, 0xffffffc0
	s_add_i32 s0, s0, 64
	s_min_i32 s30, s0, 0x100
	s_lshl_b32 s8, s2, 10
	s_add_u32 s8, s26, s8
	s_addc_u32 s9, s27, 0
	global_load_dword v0, v99, s[8:9]
	global_load_dword v1, v99, s[8:9] offset:256
	global_load_dword v2, v99, s[8:9] offset:512
	global_load_dword v3, v99, s[8:9] offset:768
	v_mad_i64_i32 v[60:61], s[10:11], s2, v98, v[58:59]
	s_add_u32 s4, s62, 0x1be00000
	s_addc_u32 s5, s63, 0
	s_mov_b64 s[6:7], s[4:5]
	s_cmpk_gt_i32 s2, 0x3fff
	s_cbranch_scc0 .Lat_ns
	s_movk_i32 s30, 0x100
	s_add_i32 s8, s2, 0xffffc000
	s_and_b32 s9, s8, 0xffffffc0
	s_addk_i32 s9, 0x3c00
	s_lshl_b32 s9, s9, 11
	s_add_u32 s4, s4, s9
	s_addc_u32 s5, s5, 0
	s_lshl_b32 s8, s8, 4
	s_and_b32 s8, s8, 0xfffffc00
	s_lshl_b32 s8, s8, 11
	s_add_u32 s6, s62, 0x1df00000
	s_addc_u32 s7, s63, 0
	s_add_u32 s6, s6, s8
	s_addc_u32 s7, s7, 0

; __device__ __forceinline__ void attn_phase(const Args& a, unsigned char* lds, int lane, int wave) {
;     ...
;             float s[8];
; #pragma unroll
;             for (int i = 0; i < 8; ++i) { float kf[16]; unpack16_fp8(kk[i], kf); float d0 = 0.f, d1 = 0.f;
; #pragma unroll
;                 for (int x = 0; x < 16; x += 2) { d0 += q[x] * kf[x]; d1 += q[x + 1] * kf[x + 1]; }
;                 float d = d0 + d1;
;                 d += __shfl_xor(d, 1); d += __shfl_xor(d, 2); d += __shfl_xor(d, 4); s[i] = d; }
.Lat_blk:
	s_barrier
	s_waitcnt vmcnt(30)
	v_cvt_pk_f32_fp8_e32 v[204:205], v132
	v_cvt_pk_f32_fp8_e32 v[206:207], v136
	v_pk_mul_f32 v[220:221], v[204:205], v[78:79]
	v_pk_mul_f32 v[222:223], v[206:207], v[78:79]
	v_cvt_pk_f32_fp8_sdwa v[208:209], v132 src0_sel:WORD_1
	v_cvt_pk_f32_fp8_sdwa v[210:211], v136 src0_sel:WORD_1
	v_pk_fma_f32 v[220:221], v[208:209], v[80:81], v[220:221]
	v_pk_fma_f32 v[222:223], v[210:211], v[80:81], v[222:223]
	v_cvt_pk_f32_fp8_e32 v[212:213], v133
	v_cvt_pk_f32_fp8_e32 v[214:215], v137
	v_pk_fma_f32 v[220:221], v[212:213], v[82:83], v[220:221]
	v_pk_fma_f32 v[222:223], v[214:215], v[82:83], v[222:223]
	v_cvt_pk_f32_fp8_sdwa v[216:217], v133 src0_sel:WORD_1
	v_cvt_pk_f32_fp8_sdwa v[218:219], v137 src0_sel:WORD_1
	v_pk_fma_f32 v[220:221], v[216:217], v[84:85], v[220:221]
	v_pk_fma_f32 v[222:223], v[218:219], v[84:85], v[222:223]
	v_cvt_pk_f32_fp8_e32 v[204:205], v134
	v_cvt_pk_f32_fp8_e32 v[206:207], v138
	v_pk_fma_f32 v[220:221], v[204:205], v[86:87], v[220:221]
	v_pk_fma_f32 v[222:223], v[206:207], v[86:87], v[222:223]
	v_cvt_pk_f32_fp8_sdwa v[208:209], v134 src0_sel:WORD_1
	v_cvt_pk_f32_fp8_sdwa v[210:211], v138 src0_sel:WORD_1
	v_pk_fma_f32 v[220:221], v[208:209], v[88:89], v[220:221]
	v_pk_fma_f32 v[222:223], v[210:211], v[88:89], v[222:223]
	v_cvt_pk_f32_fp8_e32 v[212:213], v135
	v_cvt_pk_f32_fp8_e32 v[214:215], v139
	v_pk_fma_f32 v[220:221], v[212:213], v[90:91], v[220:221]
	v_pk_fma_f32 v[222:223], v[214:215], v[90:91], v[222:223]
	v_cvt_pk_f32_fp8_sdwa v[216:217], v135 src0_sel:WORD_1
	v_cvt_pk_f32_fp8_sdwa v[218:219], v139 src0_sel:WORD_1
	v_pk_fma_f32 v[220:221], v[216:217], v[92:93], v[220:221]
	v_pk_fma_f32 v[222:223], v[218:219], v[92:93], v[222:223]
	s_waitcnt vmcnt(28)
	v_cvt_pk_f32_fp8_e32 v[204:205], v140
	v_cvt_pk_f32_fp8_e32 v[206:207], v144
	v_pk_mul_f32 v[224:225], v[204:205], v[78:79]
	v_pk_mul_f32 v[226:227], v[206:207], v[78:79]
	v_cvt_pk_f32_fp8_sdwa v[208:209], v140 src0_sel:WORD_1
	v_cvt_pk_f32_fp8_sdwa v[210:211], v144 src0_sel:WORD_1
	v_pk_fma_f32 v[224:225], v[208:209], v[80:81], v[224:225]
	v_pk_fma_f32 v[226:227], v[210:211], v[80:81], v[226:227]
	v_cvt_pk_f32_fp8_e32 v[212:213], v141
	v_cvt_pk_f32_fp8_e32 v[214:215], v145
	v_pk_fma_f32 v[224:225], v[212:213], v[82:83], v[224:225]
	v_pk_fma_f32 v[226:227], v[214:215], v[82:83], v[226:227]
	v_cvt_pk_f32_fp8_sdwa v[216:217], v141 src0_sel:WORD_1
	v_cvt_pk_f32_fp8_sdwa v[218:219], v145 src0_sel:WORD_1
	v_pk_fma_f32 v[224:225], v[216:217], v[84:85], v[224:225]
	v_pk_fma_f32 v[226:227], v[218:219], v[84:85], v[226:227]
	v_cvt_pk_f32_fp8_e32 v[204:205], v142
	v_cvt_pk_f32_fp8_e32 v[206:207], v146
	v_pk_fma_f32 v[224:225], v[204:205], v[86:87], v[224:225]
	v_pk_fma_f32 v[226:227], v[206:207], v[86:87], v[226:227]
	v_cvt_pk_f32_fp8_sdwa v[208:209], v142 src0_sel:WORD_1
	v_cvt_pk_f32_fp8_sdwa v[210:211], v146 src0_sel:WORD_1
	v_pk_fma_f32 v[224:225], v[208:209], v[88:89], v[224:225]
	v_pk_fma_f32 v[226:227], v[210:211], v[88:89], v[226:227]
	v_cvt_pk_f32_fp8_e32 v[212:213], v143
	v_cvt_pk_f32_fp8_e32 v[214:215], v147
	v_pk_fma_f32 v[224:225], v[212:213], v[90:91], v[224:225]
	v_pk_fma_f32 v[226:227], v[214:215], v[90:91], v[226:227]
	v_cvt_pk_f32_fp8_sdwa v[216:217], v143 src0_sel:WORD_1
	v_cvt_pk_f32_fp8_sdwa v[218:219], v147 src0_sel:WORD_1
	v_pk_fma_f32 v[224:225], v[216:217], v[92:93], v[224:225]
	v_pk_fma_f32 v[226:227], v[218:219], v[92:93], v[226:227]
	v_add_f32_e32 v110, v220, v221
	v_add_f32_e32 v111, v222, v223
	v_add_f32_e32 v112, v224, v225
	v_add_f32_e32 v113, v226, v227
	v_add_f32_dpp v110, v110, v110 quad_perm:[1,0,3,2] row_mask:0xf bank_mask:0xf
	v_add_f32_dpp v111, v111, v111 quad_perm:[1,0,3,2] row_mask:0xf bank_mask:0xf
	v_add_f32_dpp v112, v112, v112 quad_perm:[1,0,3,2] row_mask:0xf bank_mask:0xf
	v_add_f32_dpp v113, v113, v113 quad_perm:[1,0,3,2] row_mask:0xf bank_mask:0xf
	v_add_f32_dpp v110, v110, v110 quad_perm:[2,3,0,1] row_mask:0xf bank_mask:0xf
	v_add_f32_dpp v111, v111, v111 quad_perm:[2,3,0,1] row_mask:0xf bank_mask:0xf
	v_add_f32_dpp v112, v112, v112 quad_perm:[2,3,0,1] row_mask:0xf bank_mask:0xf
	v_add_f32_dpp v113, v113, v113 quad_perm:[2,3,0,1] row_mask:0xf bank_mask:0xf
	v_add_f32_dpp v110, v110, v110 row_half_mirror row_mask:0xf bank_mask:0xf
	v_add_f32_dpp v111, v111, v111 row_half_mirror row_mask:0xf bank_mask:0xf
	v_add_f32_dpp v112, v112, v112 row_half_mirror row_mask:0xf bank_mask:0xf
	v_add_f32_dpp v113, v113, v113 row_half_mirror row_mask:0xf bank_mask:0xf
	s_waitcnt vmcnt(26)
	v_cvt_pk_f32_fp8_e32 v[204:205], v148
	v_cvt_pk_f32_fp8_e32 v[206:207], v152
	v_pk_mul_f32 v[220:221], v[204:205], v[78:79]
	v_pk_mul_f32 v[222:223], v[206:207], v[78:79]
	v_cvt_pk_f32_fp8_sdwa v[208:209], v148 src0_sel:WORD_1
	v_cvt_pk_f32_fp8_sdwa v[210:211], v152 src0_sel:WORD_1
	v_pk_fma_f32 v[220:221], v[208:209], v[80:81], v[220:221]
	v_pk_fma_f32 v[222:223], v[210:211], v[80:81], v[222:223]
	v_cvt_pk_f32_fp8_e32 v[212:213], v149
	v_cvt_pk_f32_fp8_e32 v[214:215], v153
	v_pk_fma_f32 v[220:221], v[212:213], v[82:83], v[220:221]
	v_pk_fma_f32 v[222:223], v[214:215], v[82:83], v[222:223]
	v_cvt_pk_f32_fp8_sdwa v[216:217], v149 src0_sel:WORD_1
	v_cvt_pk_f32_fp8_sdwa v[218:219], v153 src0_sel:WORD_1
	v_pk_fma_f32 v[220:221], v[216:217], v[84:85], v[220:221]
	v_pk_fma_f32 v[222:223], v[218:219], v[84:85], v[222:223]
	v_cvt_pk_f32_fp8_e32 v[204:205], v150
	v_cvt_pk_f32_fp8_e32 v[206:207], v154
	v_pk_fma_f32 v[220:221], v[204:205], v[86:87], v[220:221]
	v_pk_fma_f32 v[222:223], v[206:207], v[86:87], v[222:223]
	v_cvt_pk_f32_fp8_sdwa v[208:209], v150 src0_sel:WORD_1
	v_cvt_pk_f32_fp8_sdwa v[210:211], v154 src0_sel:WORD_1
	v_pk_fma_f32 v[220:221], v[208:209], v[88:89], v[220:221]
	v_pk_fma_f32 v[222:223], v[210:211], v[88:89], v[222:223]
	v_cvt_pk_f32_fp8_e32 v[212:213], v151
	v_cvt_pk_f32_fp8_e32 v[214:215], v155
	v_pk_fma_f32 v[220:221], v[212:213], v[90:91], v[220:221]
	v_pk_fma_f32 v[222:223], v[214:215], v[90:91], v[222:223]
	v_cvt_pk_f32_fp8_sdwa v[216:217], v151 src0_sel:WORD_1
	v_cvt_pk_f32_fp8_sdwa v[218:219], v155 src0_sel:WORD_1
	v_pk_fma_f32 v[220:221], v[216:217], v[92:93], v[220:221]
	v_pk_fma_f32 v[222:223], v[218:219], v[92:93], v[222:223]
	s_waitcnt vmcnt(24)
; __device__ __forceinline__ void attn_phase(const Args& a, unsigned char* lds, int lane, int wave) {
;     ...
;             float s[8];
; #pragma unroll
;             for (int i = 0; i < 8; ++i) { float kf[16]; unpack16_fp8(kk[i], kf); float d0 = 0.f, d1 = 0.f;
; #pragma unroll
;                 for (int x = 0; x < 16; x += 2) { d0 += q[x] * kf[x]; d1 += q[x + 1] * kf[x + 1]; }
;                 float d = d0 + d1;
;                 d += __shfl_xor(d, 1); d += __shfl_xor(d, 2); d += __shfl_xor(d, 4); s[i] = d; }
	v_cvt_pk_f32_fp8_e32 v[204:205], v156
	v_cvt_pk_f32_fp8_e32 v[206:207], v160
	v_pk_mul_f32 v[224:225], v[204:205], v[78:79]
	v_pk_mul_f32 v[226:227], v[206:207], v[78:79]
	v_cvt_pk_f32_fp8_sdwa v[208:209], v156 src0_sel:WORD_1
	v_cvt_pk_f32_fp8_sdwa v[210:211], v160 src0_sel:WORD_1
	v_pk_fma_f32 v[224:225], v[208:209], v[80:81], v[224:225]
	v_pk_fma_f32 v[226:227], v[210:211], v[80:81], v[226:227]
	v_cvt_pk_f32_fp8_e32 v[212:213], v157
	v_cvt_pk_f32_fp8_e32 v[214:215], v161
	v_pk_fma_f32 v[224:225], v[212:213], v[82:83], v[224:225]
	v_pk_fma_f32 v[226:227], v[214:215], v[82:83], v[226:227]
	v_cvt_pk_f32_fp8_sdwa v[216:217], v157 src0_sel:WORD_1
	v_cvt_pk_f32_fp8_sdwa v[218:219], v161 src0_sel:WORD_1
	v_pk_fma_f32 v[224:225], v[216:217], v[84:85], v[224:225]
	v_pk_fma_f32 v[226:227], v[218:219], v[84:85], v[226:227]
	v_cvt_pk_f32_fp8_e32 v[204:205], v158
	v_cvt_pk_f32_fp8_e32 v[206:207], v162
	v_pk_fma_f32 v[224:225], v[204:205], v[86:87], v[224:225]
	v_pk_fma_f32 v[226:227], v[206:207], v[86:87], v[226:227]
	v_cvt_pk_f32_fp8_sdwa v[208:209], v158 src0_sel:WORD_1
	v_cvt_pk_f32_fp8_sdwa v[210:211], v162 src0_sel:WORD_1
	v_pk_fma_f32 v[224:225], v[208:209], v[88:89], v[224:225]
	v_pk_fma_f32 v[226:227], v[210:211], v[88:89], v[226:227]
	v_cvt_pk_f32_fp8_e32 v[212:213], v159
	v_cvt_pk_f32_fp8_e32 v[214:215], v163
	v_pk_fma_f32 v[224:225], v[212:213], v[90:91], v[224:225]
	v_pk_fma_f32 v[226:227], v[214:215], v[90:91], v[226:227]
	v_cvt_pk_f32_fp8_sdwa v[216:217], v159 src0_sel:WORD_1
	v_cvt_pk_f32_fp8_sdwa v[218:219], v163 src0_sel:WORD_1
	v_pk_fma_f32 v[224:225], v[216:217], v[92:93], v[224:225]
	v_pk_fma_f32 v[226:227], v[218:219], v[92:93], v[226:227]
	v_add_f32_e32 v114, v220, v221
	v_add_f32_e32 v115, v222, v223
	v_add_f32_e32 v116, v224, v225
	v_add_f32_e32 v117, v226, v227
	v_add_f32_dpp v114, v114, v114 quad_perm:[1,0,3,2] row_mask:0xf bank_mask:0xf
	v_add_f32_dpp v115, v115, v115 quad_perm:[1,0,3,2] row_mask:0xf bank_mask:0xf
	v_add_f32_dpp v116, v116, v116 quad_perm:[1,0,3,2] row_mask:0xf bank_mask:0xf
	v_add_f32_dpp v117, v117, v117 quad_perm:[1,0,3,2] row_mask:0xf bank_mask:0xf
	v_add_f32_dpp v114, v114, v114 quad_perm:[2,3,0,1] row_mask:0xf bank_mask:0xf
	v_add_f32_dpp v115, v115, v115 quad_perm:[2,3,0,1] row_mask:0xf bank_mask:0xf
	v_add_f32_dpp v116, v116, v116 quad_perm:[2,3,0,1] row_mask:0xf bank_mask:0xf
	v_add_f32_dpp v117, v117, v117 quad_perm:[2,3,0,1] row_mask:0xf bank_mask:0xf
	v_add_f32_dpp v114, v114, v114 row_half_mirror row_mask:0xf bank_mask:0xf
	v_add_f32_dpp v115, v115, v115 row_half_mirror row_mask:0xf bank_mask:0xf
	v_add_f32_dpp v116, v116, v116 row_half_mirror row_mask:0xf bank_mask:0xf
	v_add_f32_dpp v117, v117, v117 row_half_mirror row_mask:0xf bank_mask:0xf
	s_waitcnt vmcnt(22)
	v_cvt_pk_f32_fp8_e32 v[204:205], v164
	v_cvt_pk_f32_fp8_e32 v[206:207], v168
	v_pk_mul_f32 v[220:221], v[204:205], v[78:79]
	v_pk_mul_f32 v[222:223], v[206:207], v[78:79]
	v_cvt_pk_f32_fp8_sdwa v[208:209], v164 src0_sel:WORD_1
	v_cvt_pk_f32_fp8_sdwa v[210:211], v168 src0_sel:WORD_1
	v_pk_fma_f32 v[220:221], v[208:209], v[80:81], v[220:221]
	v_pk_fma_f32 v[222:223], v[210:211], v[80:81], v[222:223]
	v_cvt_pk_f32_fp8_e32 v[212:213], v165
	v_cvt_pk_f32_fp8_e32 v[214:215], v169
	v_pk_fma_f32 v[220:221], v[212:213], v[82:83], v[220:221]
	v_pk_fma_f32 v[222:223], v[214:215], v[82:83], v[222:223]
	v_cvt_pk_f32_fp8_sdwa v[216:217], v165 src0_sel:WORD_1
	v_cvt_pk_f32_fp8_sdwa v[218:219], v169 src0_sel:WORD_1
	v_pk_fma_f32 v[220:221], v[216:217], v[84:85], v[220:221]
	v_pk_fma_f32 v[222:223], v[218:219], v[84:85], v[222:223]
	v_cvt_pk_f32_fp8_e32 v[204:205], v166
	v_cvt_pk_f32_fp8_e32 v[206:207], v170
	v_pk_fma_f32 v[220:221], v[204:205], v[86:87], v[220:221]
	v_pk_fma_f32 v[222:223], v[206:207], v[86:87], v[222:223]
	v_cvt_pk_f32_fp8_sdwa v[208:209], v166 src0_sel:WORD_1
	v_cvt_pk_f32_fp8_sdwa v[210:211], v170 src0_sel:WORD_1
	v_pk_fma_f32 v[220:221], v[208:209], v[88:89], v[220:221]
	v_pk_fma_f32 v[222:223], v[210:211], v[88:89], v[222:223]
	v_cvt_pk_f32_fp8_e32 v[212:213], v167
	v_cvt_pk_f32_fp8_e32 v[214:215], v171
	v_pk_fma_f32 v[220:221], v[212:213], v[90:91], v[220:221]
	v_pk_fma_f32 v[222:223], v[214:215], v[90:91], v[222:223]
	v_cvt_pk_f32_fp8_sdwa v[216:217], v167 src0_sel:WORD_1
	v_cvt_pk_f32_fp8_sdwa v[218:219], v171 src0_sel:WORD_1
	v_pk_fma_f32 v[220:221], v[216:217], v[92:93], v[220:221]
	v_pk_fma_f32 v[222:223], v[218:219], v[92:93], v[222:223]
	s_waitcnt vmcnt(20)
; __device__ __forceinline__ void attn_phase(const Args& a, unsigned char* lds, int lane, int wave) {
;     ...
;             float s[8];
; #pragma unroll
;             for (int i = 0; i < 8; ++i) { float kf[16]; unpack16_fp8(kk[i], kf); float d0 = 0.f, d1 = 0.f;
; #pragma unroll
;                 for (int x = 0; x < 16; x += 2) { d0 += q[x] * kf[x]; d1 += q[x + 1] * kf[x + 1]; }
;                 float d = d0 + d1;
;                 d += __shfl_xor(d, 1); d += __shfl_xor(d, 2); d += __shfl_xor(d, 4); s[i] = d; }
	v_cvt_pk_f32_fp8_e32 v[204:205], v172
	v_cvt_pk_f32_fp8_e32 v[206:207], v176
	v_pk_mul_f32 v[224:225], v[204:205], v[78:79]
	v_pk_mul_f32 v[226:227], v[206:207], v[78:79]
	v_cvt_pk_f32_fp8_sdwa v[208:209], v172 src0_sel:WORD_1
	v_cvt_pk_f32_fp8_sdwa v[210:211], v176 src0_sel:WORD_1
	v_pk_fma_f32 v[224:225], v[208:209], v[80:81], v[224:225]
	v_pk_fma_f32 v[226:227], v[210:211], v[80:81], v[226:227]
	v_cvt_pk_f32_fp8_e32 v[212:213], v173
	v_cvt_pk_f32_fp8_e32 v[214:215], v177
	v_pk_fma_f32 v[224:225], v[212:213], v[82:83], v[224:225]
	v_pk_fma_f32 v[226:227], v[214:215], v[82:83], v[226:227]
	v_cvt_pk_f32_fp8_sdwa v[216:217], v173 src0_sel:WORD_1
	v_cvt_pk_f32_fp8_sdwa v[218:219], v177 src0_sel:WORD_1
	v_pk_fma_f32 v[224:225], v[216:217], v[84:85], v[224:225]
	v_pk_fma_f32 v[226:227], v[218:219], v[84:85], v[226:227]
	v_cvt_pk_f32_fp8_e32 v[204:205], v174
	v_cvt_pk_f32_fp8_e32 v[206:207], v178
	v_pk_fma_f32 v[224:225], v[204:205], v[86:87], v[224:225]
	v_pk_fma_f32 v[226:227], v[206:207], v[86:87], v[226:227]
	v_cvt_pk_f32_fp8_sdwa v[208:209], v174 src0_sel:WORD_1
	v_cvt_pk_f32_fp8_sdwa v[210:211], v178 src0_sel:WORD_1
	v_pk_fma_f32 v[224:225], v[208:209], v[88:89], v[224:225]
	v_pk_fma_f32 v[226:227], v[210:211], v[88:89], v[226:227]
	v_cvt_pk_f32_fp8_e32 v[212:213], v175
	v_cvt_pk_f32_fp8_e32 v[214:215], v179
	v_pk_fma_f32 v[224:225], v[212:213], v[90:91], v[224:225]
	v_pk_fma_f32 v[226:227], v[214:215], v[90:91], v[226:227]
	v_cvt_pk_f32_fp8_sdwa v[216:217], v175 src0_sel:WORD_1
	v_cvt_pk_f32_fp8_sdwa v[218:219], v179 src0_sel:WORD_1
	v_pk_fma_f32 v[224:225], v[216:217], v[92:93], v[224:225]
	v_pk_fma_f32 v[226:227], v[218:219], v[92:93], v[226:227]
	v_add_f32_e32 v118, v220, v221
	v_add_f32_e32 v119, v222, v223
	v_add_f32_e32 v120, v224, v225
	v_add_f32_e32 v121, v226, v227
	v_add_f32_dpp v118, v118, v118 quad_perm:[1,0,3,2] row_mask:0xf bank_mask:0xf
	v_add_f32_dpp v119, v119, v119 quad_perm:[1,0,3,2] row_mask:0xf bank_mask:0xf
	v_add_f32_dpp v120, v120, v120 quad_perm:[1,0,3,2] row_mask:0xf bank_mask:0xf
	v_add_f32_dpp v121, v121, v121 quad_perm:[1,0,3,2] row_mask:0xf bank_mask:0xf
	v_add_f32_dpp v118, v118, v118 quad_perm:[2,3,0,1] row_mask:0xf bank_mask:0xf
	v_add_f32_dpp v119, v119, v119 quad_perm:[2,3,0,1] row_mask:0xf bank_mask:0xf
	v_add_f32_dpp v120, v120, v120 quad_perm:[2,3,0,1] row_mask:0xf bank_mask:0xf
	v_add_f32_dpp v121, v121, v121 quad_perm:[2,3,0,1] row_mask:0xf bank_mask:0xf
	v_add_f32_dpp v118, v118, v118 row_half_mirror row_mask:0xf bank_mask:0xf
	v_add_f32_dpp v119, v119, v119 row_half_mirror row_mask:0xf bank_mask:0xf
	v_add_f32_dpp v120, v120, v120 row_half_mirror row_mask:0xf bank_mask:0xf
	v_add_f32_dpp v121, v121, v121 row_half_mirror row_mask:0xf bank_mask:0xf
	s_waitcnt vmcnt(18)
	v_cvt_pk_f32_fp8_e32 v[204:205], v180
	v_cvt_pk_f32_fp8_e32 v[206:207], v184
	v_pk_mul_f32 v[220:221], v[204:205], v[78:79]
	v_pk_mul_f32 v[222:223], v[206:207], v[78:79]
	v_cvt_pk_f32_fp8_sdwa v[208:209], v180 src0_sel:WORD_1
	v_cvt_pk_f32_fp8_sdwa v[210:211], v184 src0_sel:WORD_1
	v_pk_fma_f32 v[220:221], v[208:209], v[80:81], v[220:221]
	v_pk_fma_f32 v[222:223], v[210:211], v[80:81], v[222:223]
	v_cvt_pk_f32_fp8_e32 v[212:213], v181
	v_cvt_pk_f32_fp8_e32 v[214:215], v185
	v_pk_fma_f32 v[220:221], v[212:213], v[82:83], v[220:221]
	v_pk_fma_f32 v[222:223], v[214:215], v[82:83], v[222:223]
	v_cvt_pk_f32_fp8_sdwa v[216:217], v181 src0_sel:WORD_1
	v_cvt_pk_f32_fp8_sdwa v[218:219], v185 src0_sel:WORD_1
	v_pk_fma_f32 v[220:221], v[216:217], v[84:85], v[220:221]
	v_pk_fma_f32 v[222:223], v[218:219], v[84:85], v[222:223]
	v_cvt_pk_f32_fp8_e32 v[204:205], v182
	v_cvt_pk_f32_fp8_e32 v[206:207], v186
	v_pk_fma_f32 v[220:221], v[204:205], v[86:87], v[220:221]
	v_pk_fma_f32 v[222:223], v[206:207], v[86:87], v[222:223]
	v_cvt_pk_f32_fp8_sdwa v[208:209], v182 src0_sel:WORD_1
	v_cvt_pk_f32_fp8_sdwa v[210:211], v186 src0_sel:WORD_1
	v_pk_fma_f32 v[220:221], v[208:209], v[88:89], v[220:221]
	v_pk_fma_f32 v[222:223], v[210:211], v[88:89], v[222:223]
	v_cvt_pk_f32_fp8_e32 v[212:213], v183
	v_cvt_pk_f32_fp8_e32 v[214:215], v187
	v_pk_fma_f32 v[220:221], v[212:213], v[90:91], v[220:221]
	v_pk_fma_f32 v[222:223], v[214:215], v[90:91], v[222:223]
	v_cvt_pk_f32_fp8_sdwa v[216:217], v183 src0_sel:WORD_1
	v_cvt_pk_f32_fp8_sdwa v[218:219], v187 src0_sel:WORD_1
	v_pk_fma_f32 v[220:221], v[216:217], v[92:93], v[220:221]
	v_pk_fma_f32 v[222:223], v[218:219], v[92:93], v[222:223]
	s_waitcnt vmcnt(16)
; __device__ __forceinline__ void attn_phase(const Args& a, unsigned char* lds, int lane, int wave) {
;     ...
;         for (int j = 0; j < nsel; j += 8) {
;             const u32x4 ida = *(const u32x4*)(sel + j), idb = *(const u32x4*)(sel + j + 4);
;             u32x4 kk[8], vv[8];
; #pragma unroll
;             for (int i = 0; i < 8; ++i) { const int idx = (int)(i < 4 ? ida[i & 3] : idb[i & 3]); const unsigned char* kp;
;                 if (!sample) kp = KV8 + (size_t)idx * 2048;
;                 else if (idx < 1024) kp = CKV8 + (size_t)(bb * 1024 + idx) * 2048;
;                 else kp = KV8 + (size_t)(TP + bb * 64 + idx - 1024) * 2048;
;                 kk[i] = *(const u32x4*)(kp + lane * 16); vv[i] = *(const u32x4*)(kp + 1024 + lane * 16); }
;             float s[8];
; #pragma unroll
;             for (int i = 0; i < 8; ++i) { float kf[16]; unpack16_fp8(kk[i], kf); float d0 = 0.f, d1 = 0.f;
; #pragma unroll
;                 for (int x = 0; x < 16; x += 2) { d0 += q[x] * kf[x]; d1 += q[x + 1] * kf[x + 1]; }
;                 float d = d0 + d1;
;                 d += __shfl_xor(d, 1); d += __shfl_xor(d, 2); d += __shfl_xor(d, 4); s[i] = d; }
;             const float mn = fmaxf(fmaxf(fmaxf(mx, fmaxf(s[0], s[1])), fmaxf(s[2], s[3])), fmaxf(fmaxf(s[4], s[5]), fmaxf(s[6], s[7])));
;             const float al = __builtin_amdgcn_exp2f(mx - mn);
;             float p[8];
; #pragma unroll
;             for (int i = 0; i < 8; ++i) p[i] = __builtin_amdgcn_exp2f(s[i] - mn);
;             l = l * al + ((p[0] + p[1]) + (p[2] + p[3])) + ((p[4] + p[5]) + (p[6] + p[7]));
; #pragma unroll
;             for (int d = 0; d < 16; ++d) o[d] *= al;
	v_cvt_pk_f32_fp8_e32 v[204:205], v188
	v_cvt_pk_f32_fp8_e32 v[206:207], v192
	v_pk_mul_f32 v[224:225], v[204:205], v[78:79]
	v_pk_mul_f32 v[226:227], v[206:207], v[78:79]
	v_cvt_pk_f32_fp8_sdwa v[208:209], v188 src0_sel:WORD_1
	v_cvt_pk_f32_fp8_sdwa v[210:211], v192 src0_sel:WORD_1
	v_pk_fma_f32 v[224:225], v[208:209], v[80:81], v[224:225]
	v_pk_fma_f32 v[226:227], v[210:211], v[80:81], v[226:227]
	v_cvt_pk_f32_fp8_e32 v[212:213], v189
	v_cvt_pk_f32_fp8_e32 v[214:215], v193
	v_pk_fma_f32 v[224:225], v[212:213], v[82:83], v[224:225]
	v_pk_fma_f32 v[226:227], v[214:215], v[82:83], v[226:227]
	v_cvt_pk_f32_fp8_sdwa v[216:217], v189 src0_sel:WORD_1
	v_cvt_pk_f32_fp8_sdwa v[218:219], v193 src0_sel:WORD_1
	v_pk_fma_f32 v[224:225], v[216:217], v[84:85], v[224:225]
	v_pk_fma_f32 v[226:227], v[218:219], v[84:85], v[226:227]
	v_cvt_pk_f32_fp8_e32 v[204:205], v190
	v_cvt_pk_f32_fp8_e32 v[206:207], v194
	v_pk_fma_f32 v[224:225], v[204:205], v[86:87], v[224:225]
	v_pk_fma_f32 v[226:227], v[206:207], v[86:87], v[226:227]
	v_cvt_pk_f32_fp8_sdwa v[208:209], v190 src0_sel:WORD_1
	v_cvt_pk_f32_fp8_sdwa v[210:211], v194 src0_sel:WORD_1
	v_pk_fma_f32 v[224:225], v[208:209], v[88:89], v[224:225]
	v_pk_fma_f32 v[226:227], v[210:211], v[88:89], v[226:227]
	v_cvt_pk_f32_fp8_e32 v[212:213], v191
	v_cvt_pk_f32_fp8_e32 v[214:215], v195
	v_pk_fma_f32 v[224:225], v[212:213], v[90:91], v[224:225]
	v_pk_fma_f32 v[226:227], v[214:215], v[90:91], v[226:227]
	v_cvt_pk_f32_fp8_sdwa v[216:217], v191 src0_sel:WORD_1
	v_cvt_pk_f32_fp8_sdwa v[218:219], v195 src0_sel:WORD_1
	v_pk_fma_f32 v[224:225], v[216:217], v[92:93], v[224:225]
	v_pk_fma_f32 v[226:227], v[218:219], v[92:93], v[226:227]
	v_add_f32_e32 v122, v220, v221
	v_add_f32_e32 v123, v222, v223
	v_add_f32_e32 v124, v224, v225
	v_add_f32_e32 v125, v226, v227
	v_add_f32_dpp v122, v122, v122 quad_perm:[1,0,3,2] row_mask:0xf bank_mask:0xf
	v_add_f32_dpp v123, v123, v123 quad_perm:[1,0,3,2] row_mask:0xf bank_mask:0xf
	v_add_f32_dpp v124, v124, v124 quad_perm:[1,0,3,2] row_mask:0xf bank_mask:0xf
	v_add_f32_dpp v125, v125, v125 quad_perm:[1,0,3,2] row_mask:0xf bank_mask:0xf
	v_add_f32_dpp v122, v122, v122 quad_perm:[2,3,0,1] row_mask:0xf bank_mask:0xf
	v_add_f32_dpp v123, v123, v123 quad_perm:[2,3,0,1] row_mask:0xf bank_mask:0xf
	v_add_f32_dpp v124, v124, v124 quad_perm:[2,3,0,1] row_mask:0xf bank_mask:0xf
	v_add_f32_dpp v125, v125, v125 quad_perm:[2,3,0,1] row_mask:0xf bank_mask:0xf
	v_add_f32_dpp v122, v122, v122 row_half_mirror row_mask:0xf bank_mask:0xf
	v_add_f32_dpp v123, v123, v123 row_half_mirror row_mask:0xf bank_mask:0xf
	v_add_f32_dpp v124, v124, v124 row_half_mirror row_mask:0xf bank_mask:0xf
	v_add_f32_dpp v125, v125, v125 row_half_mirror row_mask:0xf bank_mask:0xf
	v_max3_f32 v228, v110, v111, v112
	v_max3_f32 v229, v113, v114, v115
	v_max3_f32 v230, v116, v117, v118
	v_max3_f32 v231, v119, v120, v121
	v_max3_f32 v232, v122, v123, v124
	v_max3_f32 v233, v125, v109, v228
	v_max3_f32 v234, v229, v230, v231
	v_max3_f32 v235, v232, v233, v234
	v_sub_f32_e32 v236, v109, v235
	v_sub_f32_e32 v110, v110, v235
	v_sub_f32_e32 v111, v111, v235
	v_sub_f32_e32 v112, v112, v235
	v_sub_f32_e32 v113, v113, v235
	v_sub_f32_e32 v114, v114, v235
	v_sub_f32_e32 v115, v115, v235
	v_sub_f32_e32 v116, v116, v235
	v_sub_f32_e32 v117, v117, v235
	v_sub_f32_e32 v118, v118, v235
	v_sub_f32_e32 v119, v119, v235
	v_sub_f32_e32 v120, v120, v235
	v_sub_f32_e32 v121, v121, v235
	v_sub_f32_e32 v122, v122, v235
	v_sub_f32_e32 v123, v123, v235
	v_sub_f32_e32 v124, v124, v235
	v_sub_f32_e32 v125, v125, v235
	v_exp_f32_e32 v244, v236
	v_exp_f32_e32 v110, v110
	v_exp_f32_e32 v111, v111
	v_exp_f32_e32 v112, v112
	v_exp_f32_e32 v113, v113
	v_exp_f32_e32 v114, v114
	v_exp_f32_e32 v115, v115
	v_exp_f32_e32 v116, v116
	v_exp_f32_e32 v117, v117
	v_exp_f32_e32 v118, v118
	v_exp_f32_e32 v119, v119
	v_exp_f32_e32 v120, v120
	v_exp_f32_e32 v121, v121
	v_exp_f32_e32 v122, v122
	v_exp_f32_e32 v123, v123
	v_exp_f32_e32 v124, v124
	v_exp_f32_e32 v125, v125
	v_mov_b32_e32 v109, v235
	v_pk_mul_f32 v[62:63], v[62:63], v[244:245] op_sel_hi:[1,0]
	v_pk_mul_f32 v[64:65], v[64:65], v[244:245] op_sel_hi:[1,0]
	v_pk_mul_f32 v[66:67], v[66:67], v[244:245] op_sel_hi:[1,0]
	v_pk_mul_f32 v[68:69], v[68:69], v[244:245] op_sel_hi:[1,0]
	v_pk_mul_f32 v[70:71], v[70:71], v[244:245] op_sel_hi:[1,0]
	v_pk_mul_f32 v[72:73], v[72:73], v[244:245] op_sel_hi:[1,0]
	v_pk_mul_f32 v[74:75], v[74:75], v[244:245] op_sel_hi:[1,0]
	v_pk_mul_f32 v[76:77], v[76:77], v[244:245] op_sel_hi:[1,0]
	v_add_f32_e32 v228, v110, v111
	v_add_f32_e32 v229, v112, v113
	v_add_f32_e32 v230, v114, v115
	v_add_f32_e32 v231, v116, v117
	v_add_f32_e32 v232, v118, v119
	v_add_f32_e32 v233, v120, v121
	v_add_f32_e32 v234, v122, v123
	v_add_f32_e32 v235, v124, v125
	v_add_f32_e32 v228, v228, v229
	v_add_f32_e32 v230, v230, v231
	v_add_f32_e32 v232, v232, v233
	v_add_f32_e32 v234, v234, v235
	v_add_f32_e32 v228, v228, v230
	v_add_f32_e32 v232, v232, v234
	v_add_f32_e32 v228, v228, v232
	v_fma_f32 v108, v108, v244, v228
	s_add_i32 s31, s31, 64
	v_mov_b32_e32 v246, s31
	ds_read_b128 v[204:207], v246
	ds_read_b128 v[208:211], v246 offset:16
	ds_read_b128 v[212:215], v246 offset:32
	ds_read_b128 v[216:219], v246 offset:48
	s_waitcnt lgkmcnt(0)
; __device__ __forceinline__ void attn_phase(const Args& a, unsigned char* lds, int lane, int wave) {
;     ...
;             const u32x4 ida = *(const u32x4*)(sel + j), idb = *(const u32x4*)(sel + j + 4);
;             u32x4 kk[8], vv[8];
; #pragma unroll
;             for (int i = 0; i < 8; ++i) { const int idx = (int)(i < 4 ? ida[i & 3] : idb[i & 3]); const unsigned char* kp;
;                 if (!sample) kp = KV8 + (size_t)idx * 2048;
;                 else if (idx < 1024) kp = CKV8 + (size_t)(bb * 1024 + idx) * 2048;
;                 else kp = KV8 + (size_t)(TP + bb * 64 + idx - 1024) * 2048;
;                 kk[i] = *(const u32x4*)(kp + lane * 16); vv[i] = *(const u32x4*)(kp + 1024 + lane * 16); }
;     ...
;             for (int i = 0; i < 8; ++i) { float vf[16]; unpack16_fp8(vv[i], vf);
; #pragma unroll
;                 for (int d = 0; d < 16; ++d) o[d] += p[i] * vf[d]; }
	v_readfirstlane_b32 s8, v204
	v_readfirstlane_b32 s9, v205
	v_readfirstlane_b32 s10, v206
	v_readfirstlane_b32 s11, v207
	v_readfirstlane_b32 s12, v208
	v_readfirstlane_b32 s13, v209
	v_readfirstlane_b32 s14, v210
	v_readfirstlane_b32 s15, v211
	v_readfirstlane_b32 s16, v212
	v_readfirstlane_b32 s17, v213
	v_readfirstlane_b32 s18, v214
	v_readfirstlane_b32 s19, v215
	v_readfirstlane_b32 s20, v216
	v_readfirstlane_b32 s21, v217
	v_readfirstlane_b32 s22, v218
	v_readfirstlane_b32 s23, v219
	s_cmp_lt_u32 s8, 0x400
	s_cselect_b32 s24, s6, s4
	s_cselect_b32 s25, s7, s5
	s_lshl_b32 s8, s8, 11
	s_add_u32 s24, s24, s8
	s_addc_u32 s25, s25, 0
	global_load_dwordx4 v[132:135], v56, s[24:25]
	s_cmp_lt_u32 s9, 0x400
	s_cselect_b32 s24, s6, s4
	s_cselect_b32 s25, s7, s5
	s_lshl_b32 s9, s9, 11
	s_add_u32 s24, s24, s9
	s_addc_u32 s25, s25, 0
	global_load_dwordx4 v[136:139], v56, s[24:25]
	s_cmp_lt_u32 s10, 0x400
	s_cselect_b32 s24, s6, s4
	s_cselect_b32 s25, s7, s5
	s_lshl_b32 s10, s10, 11
	s_add_u32 s24, s24, s10
	s_addc_u32 s25, s25, 0
	global_load_dwordx4 v[140:143], v56, s[24:25]
	s_cmp_lt_u32 s11, 0x400
	s_cselect_b32 s24, s6, s4
	s_cselect_b32 s25, s7, s5
	s_lshl_b32 s11, s11, 11
	s_add_u32 s24, s24, s11
	s_addc_u32 s25, s25, 0
	global_load_dwordx4 v[144:147], v56, s[24:25]
	s_cmp_lt_u32 s12, 0x400
	s_cselect_b32 s24, s6, s4
	s_cselect_b32 s25, s7, s5
	s_lshl_b32 s12, s12, 11
	s_add_u32 s24, s24, s12
	s_addc_u32 s25, s25, 0
	global_load_dwordx4 v[148:151], v56, s[24:25]
	s_cmp_lt_u32 s13, 0x400
	s_cselect_b32 s24, s6, s4
	s_cselect_b32 s25, s7, s5
	s_lshl_b32 s13, s13, 11
	s_add_u32 s24, s24, s13
	s_addc_u32 s25, s25, 0
	global_load_dwordx4 v[152:155], v56, s[24:25]
	s_cmp_lt_u32 s14, 0x400
	s_cselect_b32 s24, s6, s4
	s_cselect_b32 s25, s7, s5
	s_lshl_b32 s14, s14, 11
	s_add_u32 s24, s24, s14
	s_addc_u32 s25, s25, 0
	global_load_dwordx4 v[156:159], v56, s[24:25]
	s_cmp_lt_u32 s15, 0x400
	s_cselect_b32 s24, s6, s4
	s_cselect_b32 s25, s7, s5
	s_lshl_b32 s15, s15, 11
	s_add_u32 s24, s24, s15
	s_addc_u32 s25, s25, 0
	global_load_dwordx4 v[160:163], v56, s[24:25]
	s_cmp_lt_u32 s16, 0x400
	s_cselect_b32 s24, s6, s4
	s_cselect_b32 s25, s7, s5
	s_lshl_b32 s16, s16, 11
	s_add_u32 s24, s24, s16
	s_addc_u32 s25, s25, 0
	global_load_dwordx4 v[164:167], v56, s[24:25]
	s_cmp_lt_u32 s17, 0x400
	s_cselect_b32 s24, s6, s4
	s_cselect_b32 s25, s7, s5
	s_lshl_b32 s17, s17, 11
	s_add_u32 s24, s24, s17
	s_addc_u32 s25, s25, 0
	global_load_dwordx4 v[168:171], v56, s[24:25]
	s_cmp_lt_u32 s18, 0x400
	s_cselect_b32 s24, s6, s4
	s_cselect_b32 s25, s7, s5
	s_lshl_b32 s18, s18, 11
	s_add_u32 s24, s24, s18
	s_addc_u32 s25, s25, 0
	global_load_dwordx4 v[172:175], v56, s[24:25]
	s_cmp_lt_u32 s19, 0x400
	s_cselect_b32 s24, s6, s4
	s_cselect_b32 s25, s7, s5
	s_lshl_b32 s19, s19, 11
	s_add_u32 s24, s24, s19
	s_addc_u32 s25, s25, 0
	global_load_dwordx4 v[176:179], v56, s[24:25]
	s_cmp_lt_u32 s20, 0x400
	s_cselect_b32 s24, s6, s4
	s_cselect_b32 s25, s7, s5
	s_lshl_b32 s20, s20, 11
	s_add_u32 s24, s24, s20
	s_addc_u32 s25, s25, 0
	global_load_dwordx4 v[180:183], v56, s[24:25]
	s_cmp_lt_u32 s21, 0x400
	s_cselect_b32 s24, s6, s4
	s_cselect_b32 s25, s7, s5
	s_lshl_b32 s21, s21, 11
	s_add_u32 s24, s24, s21
	s_addc_u32 s25, s25, 0
	global_load_dwordx4 v[184:187], v56, s[24:25]
	s_cmp_lt_u32 s22, 0x400
	s_cselect_b32 s24, s6, s4
	s_cselect_b32 s25, s7, s5
	s_lshl_b32 s22, s22, 11
	s_add_u32 s24, s24, s22
	s_addc_u32 s25, s25, 0
	global_load_dwordx4 v[188:191], v56, s[24:25]
	s_cmp_lt_u32 s23, 0x400
	s_cselect_b32 s24, s6, s4
	s_cselect_b32 s25, s7, s5
	s_lshl_b32 s23, s23, 11
	s_add_u32 s24, s24, s23
	s_addc_u32 s25, s25, 0
	global_load_dwordx4 v[192:195], v56, s[24:25]
	s_waitcnt vmcnt(31)
	v_cvt_pk_f32_fp8_e32 v[204:205], v0
	v_cvt_pk_f32_fp8_sdwa v[206:207], v0 src0_sel:WORD_1
	v_pk_fma_f32 v[62:63], v[204:205], v[110:111], v[62:63] op_sel_hi:[1,0,1]
	v_pk_fma_f32 v[64:65], v[206:207], v[110:111], v[64:65] op_sel_hi:[1,0,1]
	v_cvt_pk_f32_fp8_e32 v[208:209], v1
	v_cvt_pk_f32_fp8_sdwa v[210:211], v1 src0_sel:WORD_1
	v_pk_fma_f32 v[66:67], v[208:209], v[110:111], v[66:67] op_sel_hi:[1,0,1]
	v_pk_fma_f32 v[68:69], v[210:211], v[110:111], v[68:69] op_sel_hi:[1,0,1]
	v_cvt_pk_f32_fp8_e32 v[212:213], v2
	v_cvt_pk_f32_fp8_sdwa v[214:215], v2 src0_sel:WORD_1
	v_pk_fma_f32 v[70:71], v[212:213], v[110:111], v[70:71] op_sel_hi:[1,0,1]
	v_pk_fma_f32 v[72:73], v[214:215], v[110:111], v[72:73] op_sel_hi:[1,0,1]
	v_cvt_pk_f32_fp8_e32 v[216:217], v3
	v_cvt_pk_f32_fp8_sdwa v[218:219], v3 src0_sel:WORD_1
	v_pk_fma_f32 v[74:75], v[216:217], v[110:111], v[74:75] op_sel_hi:[1,0,1]
	v_pk_fma_f32 v[76:77], v[218:219], v[110:111], v[76:77] op_sel_hi:[1,0,1]
	s_waitcnt vmcnt(30)
	v_cvt_pk_f32_fp8_e32 v[204:205], v4
	v_cvt_pk_f32_fp8_sdwa v[206:207], v4 src0_sel:WORD_1
	v_pk_fma_f32 v[62:63], v[204:205], v[110:111], v[62:63] op_sel:[0,1,0] op_sel_hi:[1,1,1]
	v_pk_fma_f32 v[64:65], v[206:207], v[110:111], v[64:65] op_sel:[0,1,0] op_sel_hi:[1,1,1]
	v_cvt_pk_f32_fp8_e32 v[208:209], v5
	v_cvt_pk_f32_fp8_sdwa v[210:211], v5 src0_sel:WORD_1
	v_pk_fma_f32 v[66:67], v[208:209], v[110:111], v[66:67] op_sel:[0,1,0] op_sel_hi:[1,1,1]
	v_pk_fma_f32 v[68:69], v[210:211], v[110:111], v[68:69] op_sel:[0,1,0] op_sel_hi:[1,1,1]
	v_cvt_pk_f32_fp8_e32 v[212:213], v6
	v_cvt_pk_f32_fp8_sdwa v[214:215], v6 src0_sel:WORD_1
	v_pk_fma_f32 v[70:71], v[212:213], v[110:111], v[70:71] op_sel:[0,1,0] op_sel_hi:[1,1,1]
	v_pk_fma_f32 v[72:73], v[214:215], v[110:111], v[72:73] op_sel:[0,1,0] op_sel_hi:[1,1,1]
	v_cvt_pk_f32_fp8_e32 v[216:217], v7
	v_cvt_pk_f32_fp8_sdwa v[218:219], v7 src0_sel:WORD_1
	v_pk_fma_f32 v[74:75], v[216:217], v[110:111], v[74:75] op_sel:[0,1,0] op_sel_hi:[1,1,1]
	v_pk_fma_f32 v[76:77], v[218:219], v[110:111], v[76:77] op_sel:[0,1,0] op_sel_hi:[1,1,1]
	s_waitcnt vmcnt(29)
; __device__ __forceinline__ void attn_phase(const Args& a, unsigned char* lds, int lane, int wave) {
;     ...
;             for (int i = 0; i < 8; ++i) { float vf[16]; unpack16_fp8(vv[i], vf);
; #pragma unroll
;                 for (int d = 0; d < 16; ++d) o[d] += p[i] * vf[d]; }
	v_cvt_pk_f32_fp8_e32 v[204:205], v8
	v_cvt_pk_f32_fp8_sdwa v[206:207], v8 src0_sel:WORD_1
	v_pk_fma_f32 v[62:63], v[204:205], v[112:113], v[62:63] op_sel_hi:[1,0,1]
	v_pk_fma_f32 v[64:65], v[206:207], v[112:113], v[64:65] op_sel_hi:[1,0,1]
	v_cvt_pk_f32_fp8_e32 v[208:209], v9
	v_cvt_pk_f32_fp8_sdwa v[210:211], v9 src0_sel:WORD_1
	v_pk_fma_f32 v[66:67], v[208:209], v[112:113], v[66:67] op_sel_hi:[1,0,1]
	v_pk_fma_f32 v[68:69], v[210:211], v[112:113], v[68:69] op_sel_hi:[1,0,1]
	v_cvt_pk_f32_fp8_e32 v[212:213], v10
	v_cvt_pk_f32_fp8_sdwa v[214:215], v10 src0_sel:WORD_1
	v_pk_fma_f32 v[70:71], v[212:213], v[112:113], v[70:71] op_sel_hi:[1,0,1]
	v_pk_fma_f32 v[72:73], v[214:215], v[112:113], v[72:73] op_sel_hi:[1,0,1]
	v_cvt_pk_f32_fp8_e32 v[216:217], v11
	v_cvt_pk_f32_fp8_sdwa v[218:219], v11 src0_sel:WORD_1
	v_pk_fma_f32 v[74:75], v[216:217], v[112:113], v[74:75] op_sel_hi:[1,0,1]
	v_pk_fma_f32 v[76:77], v[218:219], v[112:113], v[76:77] op_sel_hi:[1,0,1]
	s_waitcnt vmcnt(28)
	v_cvt_pk_f32_fp8_e32 v[204:205], v12
	v_cvt_pk_f32_fp8_sdwa v[206:207], v12 src0_sel:WORD_1
	v_pk_fma_f32 v[62:63], v[204:205], v[112:113], v[62:63] op_sel:[0,1,0] op_sel_hi:[1,1,1]
	v_pk_fma_f32 v[64:65], v[206:207], v[112:113], v[64:65] op_sel:[0,1,0] op_sel_hi:[1,1,1]
	v_cvt_pk_f32_fp8_e32 v[208:209], v13
	v_cvt_pk_f32_fp8_sdwa v[210:211], v13 src0_sel:WORD_1
	v_pk_fma_f32 v[66:67], v[208:209], v[112:113], v[66:67] op_sel:[0,1,0] op_sel_hi:[1,1,1]
	v_pk_fma_f32 v[68:69], v[210:211], v[112:113], v[68:69] op_sel:[0,1,0] op_sel_hi:[1,1,1]
	v_cvt_pk_f32_fp8_e32 v[212:213], v14
	v_cvt_pk_f32_fp8_sdwa v[214:215], v14 src0_sel:WORD_1
	v_pk_fma_f32 v[70:71], v[212:213], v[112:113], v[70:71] op_sel:[0,1,0] op_sel_hi:[1,1,1]
	v_pk_fma_f32 v[72:73], v[214:215], v[112:113], v[72:73] op_sel:[0,1,0] op_sel_hi:[1,1,1]
	v_cvt_pk_f32_fp8_e32 v[216:217], v15
	v_cvt_pk_f32_fp8_sdwa v[218:219], v15 src0_sel:WORD_1
	v_pk_fma_f32 v[74:75], v[216:217], v[112:113], v[74:75] op_sel:[0,1,0] op_sel_hi:[1,1,1]
	v_pk_fma_f32 v[76:77], v[218:219], v[112:113], v[76:77] op_sel:[0,1,0] op_sel_hi:[1,1,1]
	s_waitcnt vmcnt(27)
	v_cvt_pk_f32_fp8_e32 v[204:205], v16
	v_cvt_pk_f32_fp8_sdwa v[206:207], v16 src0_sel:WORD_1
	v_pk_fma_f32 v[62:63], v[204:205], v[114:115], v[62:63] op_sel_hi:[1,0,1]
	v_pk_fma_f32 v[64:65], v[206:207], v[114:115], v[64:65] op_sel_hi:[1,0,1]
	v_cvt_pk_f32_fp8_e32 v[208:209], v17
	v_cvt_pk_f32_fp8_sdwa v[210:211], v17 src0_sel:WORD_1
	v_pk_fma_f32 v[66:67], v[208:209], v[114:115], v[66:67] op_sel_hi:[1,0,1]
	v_pk_fma_f32 v[68:69], v[210:211], v[114:115], v[68:69] op_sel_hi:[1,0,1]
	v_cvt_pk_f32_fp8_e32 v[212:213], v18
	v_cvt_pk_f32_fp8_sdwa v[214:215], v18 src0_sel:WORD_1
	v_pk_fma_f32 v[70:71], v[212:213], v[114:115], v[70:71] op_sel_hi:[1,0,1]
	v_pk_fma_f32 v[72:73], v[214:215], v[114:115], v[72:73] op_sel_hi:[1,0,1]
	v_cvt_pk_f32_fp8_e32 v[216:217], v19
	v_cvt_pk_f32_fp8_sdwa v[218:219], v19 src0_sel:WORD_1
	v_pk_fma_f32 v[74:75], v[216:217], v[114:115], v[74:75] op_sel_hi:[1,0,1]
	v_pk_fma_f32 v[76:77], v[218:219], v[114:115], v[76:77] op_sel_hi:[1,0,1]
	s_waitcnt vmcnt(26)
	v_cvt_pk_f32_fp8_e32 v[204:205], v20
	v_cvt_pk_f32_fp8_sdwa v[206:207], v20 src0_sel:WORD_1
	v_pk_fma_f32 v[62:63], v[204:205], v[114:115], v[62:63] op_sel:[0,1,0] op_sel_hi:[1,1,1]
	v_pk_fma_f32 v[64:65], v[206:207], v[114:115], v[64:65] op_sel:[0,1,0] op_sel_hi:[1,1,1]
	v_cvt_pk_f32_fp8_e32 v[208:209], v21
	v_cvt_pk_f32_fp8_sdwa v[210:211], v21 src0_sel:WORD_1
	v_pk_fma_f32 v[66:67], v[208:209], v[114:115], v[66:67] op_sel:[0,1,0] op_sel_hi:[1,1,1]
	v_pk_fma_f32 v[68:69], v[210:211], v[114:115], v[68:69] op_sel:[0,1,0] op_sel_hi:[1,1,1]
	v_cvt_pk_f32_fp8_e32 v[212:213], v22
	v_cvt_pk_f32_fp8_sdwa v[214:215], v22 src0_sel:WORD_1
	v_pk_fma_f32 v[70:71], v[212:213], v[114:115], v[70:71] op_sel:[0,1,0] op_sel_hi:[1,1,1]
	v_pk_fma_f32 v[72:73], v[214:215], v[114:115], v[72:73] op_sel:[0,1,0] op_sel_hi:[1,1,1]
	v_cvt_pk_f32_fp8_e32 v[216:217], v23
	v_cvt_pk_f32_fp8_sdwa v[218:219], v23 src0_sel:WORD_1
	v_pk_fma_f32 v[74:75], v[216:217], v[114:115], v[74:75] op_sel:[0,1,0] op_sel_hi:[1,1,1]
	v_pk_fma_f32 v[76:77], v[218:219], v[114:115], v[76:77] op_sel:[0,1,0] op_sel_hi:[1,1,1]
	s_waitcnt vmcnt(25)
	v_cvt_pk_f32_fp8_e32 v[204:205], v24
	v_cvt_pk_f32_fp8_sdwa v[206:207], v24 src0_sel:WORD_1
	v_pk_fma_f32 v[62:63], v[204:205], v[116:117], v[62:63] op_sel_hi:[1,0,1]
	v_pk_fma_f32 v[64:65], v[206:207], v[116:117], v[64:65] op_sel_hi:[1,0,1]
	v_cvt_pk_f32_fp8_e32 v[208:209], v25
	v_cvt_pk_f32_fp8_sdwa v[210:211], v25 src0_sel:WORD_1
	v_pk_fma_f32 v[66:67], v[208:209], v[116:117], v[66:67] op_sel_hi:[1,0,1]
	v_pk_fma_f32 v[68:69], v[210:211], v[116:117], v[68:69] op_sel_hi:[1,0,1]
	v_cvt_pk_f32_fp8_e32 v[212:213], v26
	v_cvt_pk_f32_fp8_sdwa v[214:215], v26 src0_sel:WORD_1
	v_pk_fma_f32 v[70:71], v[212:213], v[116:117], v[70:71] op_sel_hi:[1,0,1]
	v_pk_fma_f32 v[72:73], v[214:215], v[116:117], v[72:73] op_sel_hi:[1,0,1]
	v_cvt_pk_f32_fp8_e32 v[216:217], v27
	v_cvt_pk_f32_fp8_sdwa v[218:219], v27 src0_sel:WORD_1
	v_pk_fma_f32 v[74:75], v[216:217], v[116:117], v[74:75] op_sel_hi:[1,0,1]
	v_pk_fma_f32 v[76:77], v[218:219], v[116:117], v[76:77] op_sel_hi:[1,0,1]
	s_waitcnt vmcnt(24)
; __device__ __forceinline__ void attn_phase(const Args& a, unsigned char* lds, int lane, int wave) {
;     ...
;             for (int i = 0; i < 8; ++i) { float vf[16]; unpack16_fp8(vv[i], vf);
; #pragma unroll
;                 for (int d = 0; d < 16; ++d) o[d] += p[i] * vf[d]; }
	v_cvt_pk_f32_fp8_e32 v[204:205], v28
	v_cvt_pk_f32_fp8_sdwa v[206:207], v28 src0_sel:WORD_1
	v_pk_fma_f32 v[62:63], v[204:205], v[116:117], v[62:63] op_sel:[0,1,0] op_sel_hi:[1,1,1]
	v_pk_fma_f32 v[64:65], v[206:207], v[116:117], v[64:65] op_sel:[0,1,0] op_sel_hi:[1,1,1]
	v_cvt_pk_f32_fp8_e32 v[208:209], v29
	v_cvt_pk_f32_fp8_sdwa v[210:211], v29 src0_sel:WORD_1
	v_pk_fma_f32 v[66:67], v[208:209], v[116:117], v[66:67] op_sel:[0,1,0] op_sel_hi:[1,1,1]
	v_pk_fma_f32 v[68:69], v[210:211], v[116:117], v[68:69] op_sel:[0,1,0] op_sel_hi:[1,1,1]
	v_cvt_pk_f32_fp8_e32 v[212:213], v30
	v_cvt_pk_f32_fp8_sdwa v[214:215], v30 src0_sel:WORD_1
	v_pk_fma_f32 v[70:71], v[212:213], v[116:117], v[70:71] op_sel:[0,1,0] op_sel_hi:[1,1,1]
	v_pk_fma_f32 v[72:73], v[214:215], v[116:117], v[72:73] op_sel:[0,1,0] op_sel_hi:[1,1,1]
	v_cvt_pk_f32_fp8_e32 v[216:217], v31
	v_cvt_pk_f32_fp8_sdwa v[218:219], v31 src0_sel:WORD_1
	v_pk_fma_f32 v[74:75], v[216:217], v[116:117], v[74:75] op_sel:[0,1,0] op_sel_hi:[1,1,1]
	v_pk_fma_f32 v[76:77], v[218:219], v[116:117], v[76:77] op_sel:[0,1,0] op_sel_hi:[1,1,1]
	s_waitcnt vmcnt(23)
	v_cvt_pk_f32_fp8_e32 v[204:205], v32
	v_cvt_pk_f32_fp8_sdwa v[206:207], v32 src0_sel:WORD_1
	v_pk_fma_f32 v[62:63], v[204:205], v[118:119], v[62:63] op_sel_hi:[1,0,1]
	v_pk_fma_f32 v[64:65], v[206:207], v[118:119], v[64:65] op_sel_hi:[1,0,1]
	v_cvt_pk_f32_fp8_e32 v[208:209], v33
	v_cvt_pk_f32_fp8_sdwa v[210:211], v33 src0_sel:WORD_1
	v_pk_fma_f32 v[66:67], v[208:209], v[118:119], v[66:67] op_sel_hi:[1,0,1]
	v_pk_fma_f32 v[68:69], v[210:211], v[118:119], v[68:69] op_sel_hi:[1,0,1]
	v_cvt_pk_f32_fp8_e32 v[212:213], v34
	v_cvt_pk_f32_fp8_sdwa v[214:215], v34 src0_sel:WORD_1
	v_pk_fma_f32 v[70:71], v[212:213], v[118:119], v[70:71] op_sel_hi:[1,0,1]
	v_pk_fma_f32 v[72:73], v[214:215], v[118:119], v[72:73] op_sel_hi:[1,0,1]
	v_cvt_pk_f32_fp8_e32 v[216:217], v35
	v_cvt_pk_f32_fp8_sdwa v[218:219], v35 src0_sel:WORD_1
	v_pk_fma_f32 v[74:75], v[216:217], v[118:119], v[74:75] op_sel_hi:[1,0,1]
	v_pk_fma_f32 v[76:77], v[218:219], v[118:119], v[76:77] op_sel_hi:[1,0,1]
	s_waitcnt vmcnt(22)
	v_cvt_pk_f32_fp8_e32 v[204:205], v36
	v_cvt_pk_f32_fp8_sdwa v[206:207], v36 src0_sel:WORD_1
	v_pk_fma_f32 v[62:63], v[204:205], v[118:119], v[62:63] op_sel:[0,1,0] op_sel_hi:[1,1,1]
	v_pk_fma_f32 v[64:65], v[206:207], v[118:119], v[64:65] op_sel:[0,1,0] op_sel_hi:[1,1,1]
	v_cvt_pk_f32_fp8_e32 v[208:209], v37
	v_cvt_pk_f32_fp8_sdwa v[210:211], v37 src0_sel:WORD_1
	v_pk_fma_f32 v[66:67], v[208:209], v[118:119], v[66:67] op_sel:[0,1,0] op_sel_hi:[1,1,1]
	v_pk_fma_f32 v[68:69], v[210:211], v[118:119], v[68:69] op_sel:[0,1,0] op_sel_hi:[1,1,1]
	v_cvt_pk_f32_fp8_e32 v[212:213], v38
	v_cvt_pk_f32_fp8_sdwa v[214:215], v38 src0_sel:WORD_1
	v_pk_fma_f32 v[70:71], v[212:213], v[118:119], v[70:71] op_sel:[0,1,0] op_sel_hi:[1,1,1]
	v_pk_fma_f32 v[72:73], v[214:215], v[118:119], v[72:73] op_sel:[0,1,0] op_sel_hi:[1,1,1]
	v_cvt_pk_f32_fp8_e32 v[216:217], v39
	v_cvt_pk_f32_fp8_sdwa v[218:219], v39 src0_sel:WORD_1
	v_pk_fma_f32 v[74:75], v[216:217], v[118:119], v[74:75] op_sel:[0,1,0] op_sel_hi:[1,1,1]
	v_pk_fma_f32 v[76:77], v[218:219], v[118:119], v[76:77] op_sel:[0,1,0] op_sel_hi:[1,1,1]
	s_waitcnt vmcnt(21)
	v_cvt_pk_f32_fp8_e32 v[204:205], v40
	v_cvt_pk_f32_fp8_sdwa v[206:207], v40 src0_sel:WORD_1
	v_pk_fma_f32 v[62:63], v[204:205], v[120:121], v[62:63] op_sel_hi:[1,0,1]
	v_pk_fma_f32 v[64:65], v[206:207], v[120:121], v[64:65] op_sel_hi:[1,0,1]
	v_cvt_pk_f32_fp8_e32 v[208:209], v41
	v_cvt_pk_f32_fp8_sdwa v[210:211], v41 src0_sel:WORD_1
	v_pk_fma_f32 v[66:67], v[208:209], v[120:121], v[66:67] op_sel_hi:[1,0,1]
	v_pk_fma_f32 v[68:69], v[210:211], v[120:121], v[68:69] op_sel_hi:[1,0,1]
	v_cvt_pk_f32_fp8_e32 v[212:213], v42
	v_cvt_pk_f32_fp8_sdwa v[214:215], v42 src0_sel:WORD_1
	v_pk_fma_f32 v[70:71], v[212:213], v[120:121], v[70:71] op_sel_hi:[1,0,1]
	v_pk_fma_f32 v[72:73], v[214:215], v[120:121], v[72:73] op_sel_hi:[1,0,1]
	v_cvt_pk_f32_fp8_e32 v[216:217], v43
	v_cvt_pk_f32_fp8_sdwa v[218:219], v43 src0_sel:WORD_1
	v_pk_fma_f32 v[74:75], v[216:217], v[120:121], v[74:75] op_sel_hi:[1,0,1]
	v_pk_fma_f32 v[76:77], v[218:219], v[120:121], v[76:77] op_sel_hi:[1,0,1]
	s_waitcnt vmcnt(20)
	v_cvt_pk_f32_fp8_e32 v[204:205], v44
	v_cvt_pk_f32_fp8_sdwa v[206:207], v44 src0_sel:WORD_1
	v_pk_fma_f32 v[62:63], v[204:205], v[120:121], v[62:63] op_sel:[0,1,0] op_sel_hi:[1,1,1]
	v_pk_fma_f32 v[64:65], v[206:207], v[120:121], v[64:65] op_sel:[0,1,0] op_sel_hi:[1,1,1]
	v_cvt_pk_f32_fp8_e32 v[208:209], v45
	v_cvt_pk_f32_fp8_sdwa v[210:211], v45 src0_sel:WORD_1
	v_pk_fma_f32 v[66:67], v[208:209], v[120:121], v[66:67] op_sel:[0,1,0] op_sel_hi:[1,1,1]
	v_pk_fma_f32 v[68:69], v[210:211], v[120:121], v[68:69] op_sel:[0,1,0] op_sel_hi:[1,1,1]
	v_cvt_pk_f32_fp8_e32 v[212:213], v46
	v_cvt_pk_f32_fp8_sdwa v[214:215], v46 src0_sel:WORD_1
	v_pk_fma_f32 v[70:71], v[212:213], v[120:121], v[70:71] op_sel:[0,1,0] op_sel_hi:[1,1,1]
	v_pk_fma_f32 v[72:73], v[214:215], v[120:121], v[72:73] op_sel:[0,1,0] op_sel_hi:[1,1,1]
	v_cvt_pk_f32_fp8_e32 v[216:217], v47
	v_cvt_pk_f32_fp8_sdwa v[218:219], v47 src0_sel:WORD_1
	v_pk_fma_f32 v[74:75], v[216:217], v[120:121], v[74:75] op_sel:[0,1,0] op_sel_hi:[1,1,1]
	v_pk_fma_f32 v[76:77], v[218:219], v[120:121], v[76:77] op_sel:[0,1,0] op_sel_hi:[1,1,1]
	s_waitcnt vmcnt(19)
; __device__ __forceinline__ void attn_phase(const Args& a, unsigned char* lds, int lane, int wave) {
;     ...
;             for (int i = 0; i < 8; ++i) { const int idx = (int)(i < 4 ? ida[i & 3] : idb[i & 3]); const unsigned char* kp;
;                 if (!sample) kp = KV8 + (size_t)idx * 2048;
;                 else if (idx < 1024) kp = CKV8 + (size_t)(bb * 1024 + idx) * 2048;
;                 else kp = KV8 + (size_t)(TP + bb * 64 + idx - 1024) * 2048;
;                 kk[i] = *(const u32x4*)(kp + lane * 16); vv[i] = *(const u32x4*)(kp + 1024 + lane * 16); }
;     ...
;             for (int i = 0; i < 8; ++i) { float vf[16]; unpack16_fp8(vv[i], vf);
; #pragma unroll
;                 for (int d = 0; d < 16; ++d) o[d] += p[i] * vf[d]; }
	v_cvt_pk_f32_fp8_e32 v[204:205], v48
	v_cvt_pk_f32_fp8_sdwa v[206:207], v48 src0_sel:WORD_1
	v_pk_fma_f32 v[62:63], v[204:205], v[122:123], v[62:63] op_sel_hi:[1,0,1]
	v_pk_fma_f32 v[64:65], v[206:207], v[122:123], v[64:65] op_sel_hi:[1,0,1]
	v_cvt_pk_f32_fp8_e32 v[208:209], v49
	v_cvt_pk_f32_fp8_sdwa v[210:211], v49 src0_sel:WORD_1
	v_pk_fma_f32 v[66:67], v[208:209], v[122:123], v[66:67] op_sel_hi:[1,0,1]
	v_pk_fma_f32 v[68:69], v[210:211], v[122:123], v[68:69] op_sel_hi:[1,0,1]
	v_cvt_pk_f32_fp8_e32 v[212:213], v50
	v_cvt_pk_f32_fp8_sdwa v[214:215], v50 src0_sel:WORD_1
	v_pk_fma_f32 v[70:71], v[212:213], v[122:123], v[70:71] op_sel_hi:[1,0,1]
	v_pk_fma_f32 v[72:73], v[214:215], v[122:123], v[72:73] op_sel_hi:[1,0,1]
	v_cvt_pk_f32_fp8_e32 v[216:217], v51
	v_cvt_pk_f32_fp8_sdwa v[218:219], v51 src0_sel:WORD_1
	v_pk_fma_f32 v[74:75], v[216:217], v[122:123], v[74:75] op_sel_hi:[1,0,1]
	v_pk_fma_f32 v[76:77], v[218:219], v[122:123], v[76:77] op_sel_hi:[1,0,1]
	s_waitcnt vmcnt(18)
	v_cvt_pk_f32_fp8_e32 v[204:205], v52
	v_cvt_pk_f32_fp8_sdwa v[206:207], v52 src0_sel:WORD_1
	v_pk_fma_f32 v[62:63], v[204:205], v[122:123], v[62:63] op_sel:[0,1,0] op_sel_hi:[1,1,1]
	v_pk_fma_f32 v[64:65], v[206:207], v[122:123], v[64:65] op_sel:[0,1,0] op_sel_hi:[1,1,1]
	v_cvt_pk_f32_fp8_e32 v[208:209], v53
	v_cvt_pk_f32_fp8_sdwa v[210:211], v53 src0_sel:WORD_1
	v_pk_fma_f32 v[66:67], v[208:209], v[122:123], v[66:67] op_sel:[0,1,0] op_sel_hi:[1,1,1]
	v_pk_fma_f32 v[68:69], v[210:211], v[122:123], v[68:69] op_sel:[0,1,0] op_sel_hi:[1,1,1]
	v_cvt_pk_f32_fp8_e32 v[212:213], v54
	v_cvt_pk_f32_fp8_sdwa v[214:215], v54 src0_sel:WORD_1
	v_pk_fma_f32 v[70:71], v[212:213], v[122:123], v[70:71] op_sel:[0,1,0] op_sel_hi:[1,1,1]
	v_pk_fma_f32 v[72:73], v[214:215], v[122:123], v[72:73] op_sel:[0,1,0] op_sel_hi:[1,1,1]
	v_cvt_pk_f32_fp8_e32 v[216:217], v55
	v_cvt_pk_f32_fp8_sdwa v[218:219], v55 src0_sel:WORD_1
	v_pk_fma_f32 v[74:75], v[216:217], v[122:123], v[74:75] op_sel:[0,1,0] op_sel_hi:[1,1,1]
	v_pk_fma_f32 v[76:77], v[218:219], v[122:123], v[76:77] op_sel:[0,1,0] op_sel_hi:[1,1,1]
	s_waitcnt vmcnt(17)
	v_cvt_pk_f32_fp8_e32 v[204:205], v196
	v_cvt_pk_f32_fp8_sdwa v[206:207], v196 src0_sel:WORD_1
	v_pk_fma_f32 v[62:63], v[204:205], v[124:125], v[62:63] op_sel_hi:[1,0,1]
	v_pk_fma_f32 v[64:65], v[206:207], v[124:125], v[64:65] op_sel_hi:[1,0,1]
	v_cvt_pk_f32_fp8_e32 v[208:209], v197
	v_cvt_pk_f32_fp8_sdwa v[210:211], v197 src0_sel:WORD_1
	v_pk_fma_f32 v[66:67], v[208:209], v[124:125], v[66:67] op_sel_hi:[1,0,1]
	v_pk_fma_f32 v[68:69], v[210:211], v[124:125], v[68:69] op_sel_hi:[1,0,1]
	v_cvt_pk_f32_fp8_e32 v[212:213], v198
	v_cvt_pk_f32_fp8_sdwa v[214:215], v198 src0_sel:WORD_1
	v_pk_fma_f32 v[70:71], v[212:213], v[124:125], v[70:71] op_sel_hi:[1,0,1]
	v_pk_fma_f32 v[72:73], v[214:215], v[124:125], v[72:73] op_sel_hi:[1,0,1]
	v_cvt_pk_f32_fp8_e32 v[216:217], v199
	v_cvt_pk_f32_fp8_sdwa v[218:219], v199 src0_sel:WORD_1
	v_pk_fma_f32 v[74:75], v[216:217], v[124:125], v[74:75] op_sel_hi:[1,0,1]
	v_pk_fma_f32 v[76:77], v[218:219], v[124:125], v[76:77] op_sel_hi:[1,0,1]
	s_waitcnt vmcnt(16)
	v_cvt_pk_f32_fp8_e32 v[204:205], v200
	v_cvt_pk_f32_fp8_sdwa v[206:207], v200 src0_sel:WORD_1
	v_pk_fma_f32 v[62:63], v[204:205], v[124:125], v[62:63] op_sel:[0,1,0] op_sel_hi:[1,1,1]
	v_pk_fma_f32 v[64:65], v[206:207], v[124:125], v[64:65] op_sel:[0,1,0] op_sel_hi:[1,1,1]
	v_cvt_pk_f32_fp8_e32 v[208:209], v201
	v_cvt_pk_f32_fp8_sdwa v[210:211], v201 src0_sel:WORD_1
	v_pk_fma_f32 v[66:67], v[208:209], v[124:125], v[66:67] op_sel:[0,1,0] op_sel_hi:[1,1,1]
	v_pk_fma_f32 v[68:69], v[210:211], v[124:125], v[68:69] op_sel:[0,1,0] op_sel_hi:[1,1,1]
	v_cvt_pk_f32_fp8_e32 v[212:213], v202
	v_cvt_pk_f32_fp8_sdwa v[214:215], v202 src0_sel:WORD_1
	v_pk_fma_f32 v[70:71], v[212:213], v[124:125], v[70:71] op_sel:[0,1,0] op_sel_hi:[1,1,1]
	v_pk_fma_f32 v[72:73], v[214:215], v[124:125], v[72:73] op_sel:[0,1,0] op_sel_hi:[1,1,1]
	v_cvt_pk_f32_fp8_e32 v[216:217], v203
	v_cvt_pk_f32_fp8_sdwa v[218:219], v203 src0_sel:WORD_1
	v_pk_fma_f32 v[74:75], v[216:217], v[124:125], v[74:75] op_sel:[0,1,0] op_sel_hi:[1,1,1]
	v_pk_fma_f32 v[76:77], v[218:219], v[124:125], v[76:77] op_sel:[0,1,0] op_sel_hi:[1,1,1]
	s_cmp_lt_u32 s8, 0x200000
	s_cselect_b32 s24, s6, s4
	s_cselect_b32 s25, s7, s5
	s_add_u32 s24, s24, s8
	s_addc_u32 s25, s25, 0
	global_load_dwordx4 v[0:3], v56, s[24:25] offset:1024
	s_cmp_lt_u32 s9, 0x200000
	s_cselect_b32 s24, s6, s4
	s_cselect_b32 s25, s7, s5
	s_add_u32 s24, s24, s9
	s_addc_u32 s25, s25, 0
	global_load_dwordx4 v[4:7], v56, s[24:25] offset:1024
	s_cmp_lt_u32 s10, 0x200000
	s_cselect_b32 s24, s6, s4
	s_cselect_b32 s25, s7, s5
	s_add_u32 s24, s24, s10
	s_addc_u32 s25, s25, 0
	global_load_dwordx4 v[8:11], v56, s[24:25] offset:1024
	s_cmp_lt_u32 s11, 0x200000
	s_cselect_b32 s24, s6, s4
	s_cselect_b32 s25, s7, s5
	s_add_u32 s24, s24, s11
	s_addc_u32 s25, s25, 0
	global_load_dwordx4 v[12:15], v56, s[24:25] offset:1024
	s_cmp_lt_u32 s12, 0x200000
	s_cselect_b32 s24, s6, s4
	s_cselect_b32 s25, s7, s5
	s_add_u32 s24, s24, s12
	s_addc_u32 s25, s25, 0
	global_load_dwordx4 v[16:19], v56, s[24:25] offset:1024
	s_cmp_lt_u32 s13, 0x200000
	s_cselect_b32 s24, s6, s4
	s_cselect_b32 s25, s7, s5
	s_add_u32 s24, s24, s13
	s_addc_u32 s25, s25, 0
	global_load_dwordx4 v[20:23], v56, s[24:25] offset:1024
	s_cmp_lt_u32 s14, 0x200000
	s_cselect_b32 s24, s6, s4
	s_cselect_b32 s25, s7, s5
	s_add_u32 s24, s24, s14
	s_addc_u32 s25, s25, 0
	global_load_dwordx4 v[24:27], v56, s[24:25] offset:1024
	s_cmp_lt_u32 s15, 0x200000
	s_cselect_b32 s24, s6, s4
	s_cselect_b32 s25, s7, s5
	s_add_u32 s24, s24, s15
	s_addc_u32 s25, s25, 0
; __device__ __forceinline__ void attn_phase(const Args& a, unsigned char* lds, int lane, int wave) {
;     ...
;             for (int i = 0; i < 8; ++i) { const int idx = (int)(i < 4 ? ida[i & 3] : idb[i & 3]); const unsigned char* kp;
;                 if (!sample) kp = KV8 + (size_t)idx * 2048;
;                 else if (idx < 1024) kp = CKV8 + (size_t)(bb * 1024 + idx) * 2048;
;                 else kp = KV8 + (size_t)(TP + bb * 64 + idx - 1024) * 2048;
;                 kk[i] = *(const u32x4*)(kp + lane * 16); vv[i] = *(const u32x4*)(kp + 1024 + lane * 16); }
;             float s[8];
; #pragma unroll
;             for (int i = 0; i < 8; ++i) { float kf[16]; unpack16_fp8(kk[i], kf); float d0 = 0.f, d1 = 0.f;
; #pragma unroll
;                 for (int x = 0; x < 16; x += 2) { d0 += q[x] * kf[x]; d1 += q[x + 1] * kf[x + 1]; }
;                 float d = d0 + d1;
;                 d += __shfl_xor(d, 1); d += __shfl_xor(d, 2); d += __shfl_xor(d, 4); s[i] = d; }
	global_load_dwordx4 v[28:31], v56, s[24:25] offset:1024
	s_cmp_lt_u32 s16, 0x200000
	s_cselect_b32 s24, s6, s4
	s_cselect_b32 s25, s7, s5
	s_add_u32 s24, s24, s16
	s_addc_u32 s25, s25, 0
	global_load_dwordx4 v[32:35], v56, s[24:25] offset:1024
	s_cmp_lt_u32 s17, 0x200000
	s_cselect_b32 s24, s6, s4
	s_cselect_b32 s25, s7, s5
	s_add_u32 s24, s24, s17
	s_addc_u32 s25, s25, 0
	global_load_dwordx4 v[36:39], v56, s[24:25] offset:1024
	s_cmp_lt_u32 s18, 0x200000
	s_cselect_b32 s24, s6, s4
	s_cselect_b32 s25, s7, s5
	s_add_u32 s24, s24, s18
	s_addc_u32 s25, s25, 0
	global_load_dwordx4 v[40:43], v56, s[24:25] offset:1024
	s_cmp_lt_u32 s19, 0x200000
	s_cselect_b32 s24, s6, s4
	s_cselect_b32 s25, s7, s5
	s_add_u32 s24, s24, s19
	s_addc_u32 s25, s25, 0
	global_load_dwordx4 v[44:47], v56, s[24:25] offset:1024
	s_cmp_lt_u32 s20, 0x200000
	s_cselect_b32 s24, s6, s4
	s_cselect_b32 s25, s7, s5
	s_add_u32 s24, s24, s20
	s_addc_u32 s25, s25, 0
	global_load_dwordx4 v[48:51], v56, s[24:25] offset:1024
	s_cmp_lt_u32 s21, 0x200000
	s_cselect_b32 s24, s6, s4
	s_cselect_b32 s25, s7, s5
	s_add_u32 s24, s24, s21
	s_addc_u32 s25, s25, 0
	global_load_dwordx4 v[52:55], v56, s[24:25] offset:1024
	s_cmp_lt_u32 s22, 0x200000
	s_cselect_b32 s24, s6, s4
	s_cselect_b32 s25, s7, s5
	s_add_u32 s24, s24, s22
	s_addc_u32 s25, s25, 0
	global_load_dwordx4 v[196:199], v56, s[24:25] offset:1024
	s_cmp_lt_u32 s23, 0x200000
	s_cselect_b32 s24, s6, s4
	s_cselect_b32 s25, s7, s5
	s_add_u32 s24, s24, s23
	s_addc_u32 s25, s25, 0
	global_load_dwordx4 v[200:203], v56, s[24:25] offset:1024
	s_add_i32 s3, s3, -1
	s_cmp_lg_u32 s3, 0
	s_cbranch_scc1 .Lat_blk
	s_waitcnt vmcnt(30)
	v_cvt_pk_f32_fp8_e32 v[204:205], v132
	v_cvt_pk_f32_fp8_e32 v[206:207], v136
	v_pk_mul_f32 v[220:221], v[204:205], v[78:79]
	v_pk_mul_f32 v[222:223], v[206:207], v[78:79]
	v_cvt_pk_f32_fp8_sdwa v[208:209], v132 src0_sel:WORD_1
	v_cvt_pk_f32_fp8_sdwa v[210:211], v136 src0_sel:WORD_1
	v_pk_fma_f32 v[220:221], v[208:209], v[80:81], v[220:221]
	v_pk_fma_f32 v[222:223], v[210:211], v[80:81], v[222:223]
	v_cvt_pk_f32_fp8_e32 v[212:213], v133
	v_cvt_pk_f32_fp8_e32 v[214:215], v137
	v_pk_fma_f32 v[220:221], v[212:213], v[82:83], v[220:221]
	v_pk_fma_f32 v[222:223], v[214:215], v[82:83], v[222:223]
	v_cvt_pk_f32_fp8_sdwa v[216:217], v133 src0_sel:WORD_1
	v_cvt_pk_f32_fp8_sdwa v[218:219], v137 src0_sel:WORD_1
	v_pk_fma_f32 v[220:221], v[216:217], v[84:85], v[220:221]
	v_pk_fma_f32 v[222:223], v[218:219], v[84:85], v[222:223]
	v_cvt_pk_f32_fp8_e32 v[204:205], v134
	v_cvt_pk_f32_fp8_e32 v[206:207], v138
	v_pk_fma_f32 v[220:221], v[204:205], v[86:87], v[220:221]
	v_pk_fma_f32 v[222:223], v[206:207], v[86:87], v[222:223]
	v_cvt_pk_f32_fp8_sdwa v[208:209], v134 src0_sel:WORD_1
	v_cvt_pk_f32_fp8_sdwa v[210:211], v138 src0_sel:WORD_1
	v_pk_fma_f32 v[220:221], v[208:209], v[88:89], v[220:221]
	v_pk_fma_f32 v[222:223], v[210:211], v[88:89], v[222:223]
	v_cvt_pk_f32_fp8_e32 v[212:213], v135
	v_cvt_pk_f32_fp8_e32 v[214:215], v139
	v_pk_fma_f32 v[220:221], v[212:213], v[90:91], v[220:221]
	v_pk_fma_f32 v[222:223], v[214:215], v[90:91], v[222:223]
	v_cvt_pk_f32_fp8_sdwa v[216:217], v135 src0_sel:WORD_1
	v_cvt_pk_f32_fp8_sdwa v[218:219], v139 src0_sel:WORD_1
	v_pk_fma_f32 v[220:221], v[216:217], v[92:93], v[220:221]
	v_pk_fma_f32 v[222:223], v[218:219], v[92:93], v[222:223]
	s_waitcnt vmcnt(28)
	v_cvt_pk_f32_fp8_e32 v[204:205], v140
	v_cvt_pk_f32_fp8_e32 v[206:207], v144
	v_pk_mul_f32 v[224:225], v[204:205], v[78:79]
	v_pk_mul_f32 v[226:227], v[206:207], v[78:79]
	v_cvt_pk_f32_fp8_sdwa v[208:209], v140 src0_sel:WORD_1
	v_cvt_pk_f32_fp8_sdwa v[210:211], v144 src0_sel:WORD_1
	v_pk_fma_f32 v[224:225], v[208:209], v[80:81], v[224:225]
	v_pk_fma_f32 v[226:227], v[210:211], v[80:81], v[226:227]
	v_cvt_pk_f32_fp8_e32 v[212:213], v141
	v_cvt_pk_f32_fp8_e32 v[214:215], v145
	v_pk_fma_f32 v[224:225], v[212:213], v[82:83], v[224:225]
	v_pk_fma_f32 v[226:227], v[214:215], v[82:83], v[226:227]
	v_cvt_pk_f32_fp8_sdwa v[216:217], v141 src0_sel:WORD_1
	v_cvt_pk_f32_fp8_sdwa v[218:219], v145 src0_sel:WORD_1
	v_pk_fma_f32 v[224:225], v[216:217], v[84:85], v[224:225]
	v_pk_fma_f32 v[226:227], v[218:219], v[84:85], v[226:227]
	v_cvt_pk_f32_fp8_e32 v[204:205], v142
	v_cvt_pk_f32_fp8_e32 v[206:207], v146
	v_pk_fma_f32 v[224:225], v[204:205], v[86:87], v[224:225]
	v_pk_fma_f32 v[226:227], v[206:207], v[86:87], v[226:227]
	v_cvt_pk_f32_fp8_sdwa v[208:209], v142 src0_sel:WORD_1
	v_cvt_pk_f32_fp8_sdwa v[210:211], v146 src0_sel:WORD_1
	v_pk_fma_f32 v[224:225], v[208:209], v[88:89], v[224:225]
	v_pk_fma_f32 v[226:227], v[210:211], v[88:89], v[226:227]
	v_cvt_pk_f32_fp8_e32 v[212:213], v143
	v_cvt_pk_f32_fp8_e32 v[214:215], v147
	v_pk_fma_f32 v[224:225], v[212:213], v[90:91], v[224:225]
	v_pk_fma_f32 v[226:227], v[214:215], v[90:91], v[226:227]
	v_cvt_pk_f32_fp8_sdwa v[216:217], v143 src0_sel:WORD_1
	v_cvt_pk_f32_fp8_sdwa v[218:219], v147 src0_sel:WORD_1
	v_pk_fma_f32 v[224:225], v[216:217], v[92:93], v[224:225]
	v_pk_fma_f32 v[226:227], v[218:219], v[92:93], v[226:227]
	v_add_f32_e32 v110, v220, v221
	v_add_f32_e32 v111, v222, v223
	v_add_f32_e32 v112, v224, v225
	v_add_f32_e32 v113, v226, v227
	v_add_f32_dpp v110, v110, v110 quad_perm:[1,0,3,2] row_mask:0xf bank_mask:0xf
	v_add_f32_dpp v111, v111, v111 quad_perm:[1,0,3,2] row_mask:0xf bank_mask:0xf
	v_add_f32_dpp v112, v112, v112 quad_perm:[1,0,3,2] row_mask:0xf bank_mask:0xf
	v_add_f32_dpp v113, v113, v113 quad_perm:[1,0,3,2] row_mask:0xf bank_mask:0xf
	v_add_f32_dpp v110, v110, v110 quad_perm:[2,3,0,1] row_mask:0xf bank_mask:0xf
	v_add_f32_dpp v111, v111, v111 quad_perm:[2,3,0,1] row_mask:0xf bank_mask:0xf
	v_add_f32_dpp v112, v112, v112 quad_perm:[2,3,0,1] row_mask:0xf bank_mask:0xf
	v_add_f32_dpp v113, v113, v113 quad_perm:[2,3,0,1] row_mask:0xf bank_mask:0xf
	v_add_f32_dpp v110, v110, v110 row_half_mirror row_mask:0xf bank_mask:0xf
	v_add_f32_dpp v111, v111, v111 row_half_mirror row_mask:0xf bank_mask:0xf
	v_add_f32_dpp v112, v112, v112 row_half_mirror row_mask:0xf bank_mask:0xf
	v_add_f32_dpp v113, v113, v113 row_half_mirror row_mask:0xf bank_mask:0xf
	s_waitcnt vmcnt(26)
; __device__ __forceinline__ void attn_phase(const Args& a, unsigned char* lds, int lane, int wave) {
;     ...
;             float s[8];
; #pragma unroll
;             for (int i = 0; i < 8; ++i) { float kf[16]; unpack16_fp8(kk[i], kf); float d0 = 0.f, d1 = 0.f;
; #pragma unroll
;                 for (int x = 0; x < 16; x += 2) { d0 += q[x] * kf[x]; d1 += q[x + 1] * kf[x + 1]; }
;                 float d = d0 + d1;
;                 d += __shfl_xor(d, 1); d += __shfl_xor(d, 2); d += __shfl_xor(d, 4); s[i] = d; }
	v_cvt_pk_f32_fp8_e32 v[204:205], v148
	v_cvt_pk_f32_fp8_e32 v[206:207], v152
	v_pk_mul_f32 v[220:221], v[204:205], v[78:79]
	v_pk_mul_f32 v[222:223], v[206:207], v[78:79]
	v_cvt_pk_f32_fp8_sdwa v[208:209], v148 src0_sel:WORD_1
	v_cvt_pk_f32_fp8_sdwa v[210:211], v152 src0_sel:WORD_1
	v_pk_fma_f32 v[220:221], v[208:209], v[80:81], v[220:221]
	v_pk_fma_f32 v[222:223], v[210:211], v[80:81], v[222:223]
	v_cvt_pk_f32_fp8_e32 v[212:213], v149
	v_cvt_pk_f32_fp8_e32 v[214:215], v153
	v_pk_fma_f32 v[220:221], v[212:213], v[82:83], v[220:221]
	v_pk_fma_f32 v[222:223], v[214:215], v[82:83], v[222:223]
	v_cvt_pk_f32_fp8_sdwa v[216:217], v149 src0_sel:WORD_1
	v_cvt_pk_f32_fp8_sdwa v[218:219], v153 src0_sel:WORD_1
	v_pk_fma_f32 v[220:221], v[216:217], v[84:85], v[220:221]
	v_pk_fma_f32 v[222:223], v[218:219], v[84:85], v[222:223]
	v_cvt_pk_f32_fp8_e32 v[204:205], v150
	v_cvt_pk_f32_fp8_e32 v[206:207], v154
	v_pk_fma_f32 v[220:221], v[204:205], v[86:87], v[220:221]
	v_pk_fma_f32 v[222:223], v[206:207], v[86:87], v[222:223]
	v_cvt_pk_f32_fp8_sdwa v[208:209], v150 src0_sel:WORD_1
	v_cvt_pk_f32_fp8_sdwa v[210:211], v154 src0_sel:WORD_1
	v_pk_fma_f32 v[220:221], v[208:209], v[88:89], v[220:221]
	v_pk_fma_f32 v[222:223], v[210:211], v[88:89], v[222:223]
	v_cvt_pk_f32_fp8_e32 v[212:213], v151
	v_cvt_pk_f32_fp8_e32 v[214:215], v155
	v_pk_fma_f32 v[220:221], v[212:213], v[90:91], v[220:221]
	v_pk_fma_f32 v[222:223], v[214:215], v[90:91], v[222:223]
	v_cvt_pk_f32_fp8_sdwa v[216:217], v151 src0_sel:WORD_1
	v_cvt_pk_f32_fp8_sdwa v[218:219], v155 src0_sel:WORD_1
	v_pk_fma_f32 v[220:221], v[216:217], v[92:93], v[220:221]
	v_pk_fma_f32 v[222:223], v[218:219], v[92:93], v[222:223]
	s_waitcnt vmcnt(24)
	v_cvt_pk_f32_fp8_e32 v[204:205], v156
	v_cvt_pk_f32_fp8_e32 v[206:207], v160
	v_pk_mul_f32 v[224:225], v[204:205], v[78:79]
	v_pk_mul_f32 v[226:227], v[206:207], v[78:79]
	v_cvt_pk_f32_fp8_sdwa v[208:209], v156 src0_sel:WORD_1
	v_cvt_pk_f32_fp8_sdwa v[210:211], v160 src0_sel:WORD_1
	v_pk_fma_f32 v[224:225], v[208:209], v[80:81], v[224:225]
	v_pk_fma_f32 v[226:227], v[210:211], v[80:81], v[226:227]
	v_cvt_pk_f32_fp8_e32 v[212:213], v157
	v_cvt_pk_f32_fp8_e32 v[214:215], v161
	v_pk_fma_f32 v[224:225], v[212:213], v[82:83], v[224:225]
	v_pk_fma_f32 v[226:227], v[214:215], v[82:83], v[226:227]
	v_cvt_pk_f32_fp8_sdwa v[216:217], v157 src0_sel:WORD_1
	v_cvt_pk_f32_fp8_sdwa v[218:219], v161 src0_sel:WORD_1
	v_pk_fma_f32 v[224:225], v[216:217], v[84:85], v[224:225]
	v_pk_fma_f32 v[226:227], v[218:219], v[84:85], v[226:227]
	v_cvt_pk_f32_fp8_e32 v[204:205], v158
	v_cvt_pk_f32_fp8_e32 v[206:207], v162
	v_pk_fma_f32 v[224:225], v[204:205], v[86:87], v[224:225]
	v_pk_fma_f32 v[226:227], v[206:207], v[86:87], v[226:227]
	v_cvt_pk_f32_fp8_sdwa v[208:209], v158 src0_sel:WORD_1
	v_cvt_pk_f32_fp8_sdwa v[210:211], v162 src0_sel:WORD_1
	v_pk_fma_f32 v[224:225], v[208:209], v[88:89], v[224:225]
	v_pk_fma_f32 v[226:227], v[210:211], v[88:89], v[226:227]
	v_cvt_pk_f32_fp8_e32 v[212:213], v159
	v_cvt_pk_f32_fp8_e32 v[214:215], v163
	v_pk_fma_f32 v[224:225], v[212:213], v[90:91], v[224:225]
	v_pk_fma_f32 v[226:227], v[214:215], v[90:91], v[226:227]
	v_cvt_pk_f32_fp8_sdwa v[216:217], v159 src0_sel:WORD_1
	v_cvt_pk_f32_fp8_sdwa v[218:219], v163 src0_sel:WORD_1
	v_pk_fma_f32 v[224:225], v[216:217], v[92:93], v[224:225]
	v_pk_fma_f32 v[226:227], v[218:219], v[92:93], v[226:227]
	v_add_f32_e32 v114, v220, v221
	v_add_f32_e32 v115, v222, v223
	v_add_f32_e32 v116, v224, v225
	v_add_f32_e32 v117, v226, v227
	v_add_f32_dpp v114, v114, v114 quad_perm:[1,0,3,2] row_mask:0xf bank_mask:0xf
	v_add_f32_dpp v115, v115, v115 quad_perm:[1,0,3,2] row_mask:0xf bank_mask:0xf
	v_add_f32_dpp v116, v116, v116 quad_perm:[1,0,3,2] row_mask:0xf bank_mask:0xf
	v_add_f32_dpp v117, v117, v117 quad_perm:[1,0,3,2] row_mask:0xf bank_mask:0xf
	v_add_f32_dpp v114, v114, v114 quad_perm:[2,3,0,1] row_mask:0xf bank_mask:0xf
	v_add_f32_dpp v115, v115, v115 quad_perm:[2,3,0,1] row_mask:0xf bank_mask:0xf
	v_add_f32_dpp v116, v116, v116 quad_perm:[2,3,0,1] row_mask:0xf bank_mask:0xf
	v_add_f32_dpp v117, v117, v117 quad_perm:[2,3,0,1] row_mask:0xf bank_mask:0xf
	v_add_f32_dpp v114, v114, v114 row_half_mirror row_mask:0xf bank_mask:0xf
	v_add_f32_dpp v115, v115, v115 row_half_mirror row_mask:0xf bank_mask:0xf
	v_add_f32_dpp v116, v116, v116 row_half_mirror row_mask:0xf bank_mask:0xf
	v_add_f32_dpp v117, v117, v117 row_half_mirror row_mask:0xf bank_mask:0xf
	s_waitcnt vmcnt(22)
	v_cvt_pk_f32_fp8_e32 v[204:205], v164
	v_cvt_pk_f32_fp8_e32 v[206:207], v168
	v_pk_mul_f32 v[220:221], v[204:205], v[78:79]
	v_pk_mul_f32 v[222:223], v[206:207], v[78:79]
	v_cvt_pk_f32_fp8_sdwa v[208:209], v164 src0_sel:WORD_1
	v_cvt_pk_f32_fp8_sdwa v[210:211], v168 src0_sel:WORD_1
	v_pk_fma_f32 v[220:221], v[208:209], v[80:81], v[220:221]
	v_pk_fma_f32 v[222:223], v[210:211], v[80:81], v[222:223]
	v_cvt_pk_f32_fp8_e32 v[212:213], v165
	v_cvt_pk_f32_fp8_e32 v[214:215], v169
	v_pk_fma_f32 v[220:221], v[212:213], v[82:83], v[220:221]
	v_pk_fma_f32 v[222:223], v[214:215], v[82:83], v[222:223]
	v_cvt_pk_f32_fp8_sdwa v[216:217], v165 src0_sel:WORD_1
	v_cvt_pk_f32_fp8_sdwa v[218:219], v169 src0_sel:WORD_1
	v_pk_fma_f32 v[220:221], v[216:217], v[84:85], v[220:221]
	v_pk_fma_f32 v[222:223], v[218:219], v[84:85], v[222:223]
	v_cvt_pk_f32_fp8_e32 v[204:205], v166
	v_cvt_pk_f32_fp8_e32 v[206:207], v170
	v_pk_fma_f32 v[220:221], v[204:205], v[86:87], v[220:221]
	v_pk_fma_f32 v[222:223], v[206:207], v[86:87], v[222:223]
	v_cvt_pk_f32_fp8_sdwa v[208:209], v166 src0_sel:WORD_1
	v_cvt_pk_f32_fp8_sdwa v[210:211], v170 src0_sel:WORD_1
	v_pk_fma_f32 v[220:221], v[208:209], v[88:89], v[220:221]
	v_pk_fma_f32 v[222:223], v[210:211], v[88:89], v[222:223]
	v_cvt_pk_f32_fp8_e32 v[212:213], v167
	v_cvt_pk_f32_fp8_e32 v[214:215], v171
	v_pk_fma_f32 v[220:221], v[212:213], v[90:91], v[220:221]
	v_pk_fma_f32 v[222:223], v[214:215], v[90:91], v[222:223]
	v_cvt_pk_f32_fp8_sdwa v[216:217], v167 src0_sel:WORD_1
	v_cvt_pk_f32_fp8_sdwa v[218:219], v171 src0_sel:WORD_1
	v_pk_fma_f32 v[220:221], v[216:217], v[92:93], v[220:221]
	v_pk_fma_f32 v[222:223], v[218:219], v[92:93], v[222:223]
	s_waitcnt vmcnt(20)
; __device__ __forceinline__ void attn_phase(const Args& a, unsigned char* lds, int lane, int wave) {
;     ...
;             float s[8];
; #pragma unroll
;             for (int i = 0; i < 8; ++i) { float kf[16]; unpack16_fp8(kk[i], kf); float d0 = 0.f, d1 = 0.f;
; #pragma unroll
;                 for (int x = 0; x < 16; x += 2) { d0 += q[x] * kf[x]; d1 += q[x + 1] * kf[x + 1]; }
;                 float d = d0 + d1;
;                 d += __shfl_xor(d, 1); d += __shfl_xor(d, 2); d += __shfl_xor(d, 4); s[i] = d; }
	v_cvt_pk_f32_fp8_e32 v[204:205], v172
	v_cvt_pk_f32_fp8_e32 v[206:207], v176
	v_pk_mul_f32 v[224:225], v[204:205], v[78:79]
	v_pk_mul_f32 v[226:227], v[206:207], v[78:79]
	v_cvt_pk_f32_fp8_sdwa v[208:209], v172 src0_sel:WORD_1
	v_cvt_pk_f32_fp8_sdwa v[210:211], v176 src0_sel:WORD_1
	v_pk_fma_f32 v[224:225], v[208:209], v[80:81], v[224:225]
	v_pk_fma_f32 v[226:227], v[210:211], v[80:81], v[226:227]
	v_cvt_pk_f32_fp8_e32 v[212:213], v173
	v_cvt_pk_f32_fp8_e32 v[214:215], v177
	v_pk_fma_f32 v[224:225], v[212:213], v[82:83], v[224:225]
	v_pk_fma_f32 v[226:227], v[214:215], v[82:83], v[226:227]
	v_cvt_pk_f32_fp8_sdwa v[216:217], v173 src0_sel:WORD_1
	v_cvt_pk_f32_fp8_sdwa v[218:219], v177 src0_sel:WORD_1
	v_pk_fma_f32 v[224:225], v[216:217], v[84:85], v[224:225]
	v_pk_fma_f32 v[226:227], v[218:219], v[84:85], v[226:227]
	v_cvt_pk_f32_fp8_e32 v[204:205], v174
	v_cvt_pk_f32_fp8_e32 v[206:207], v178
	v_pk_fma_f32 v[224:225], v[204:205], v[86:87], v[224:225]
	v_pk_fma_f32 v[226:227], v[206:207], v[86:87], v[226:227]
	v_cvt_pk_f32_fp8_sdwa v[208:209], v174 src0_sel:WORD_1
	v_cvt_pk_f32_fp8_sdwa v[210:211], v178 src0_sel:WORD_1
	v_pk_fma_f32 v[224:225], v[208:209], v[88:89], v[224:225]
	v_pk_fma_f32 v[226:227], v[210:211], v[88:89], v[226:227]
	v_cvt_pk_f32_fp8_e32 v[212:213], v175
	v_cvt_pk_f32_fp8_e32 v[214:215], v179
	v_pk_fma_f32 v[224:225], v[212:213], v[90:91], v[224:225]
	v_pk_fma_f32 v[226:227], v[214:215], v[90:91], v[226:227]
	v_cvt_pk_f32_fp8_sdwa v[216:217], v175 src0_sel:WORD_1
	v_cvt_pk_f32_fp8_sdwa v[218:219], v179 src0_sel:WORD_1
	v_pk_fma_f32 v[224:225], v[216:217], v[92:93], v[224:225]
	v_pk_fma_f32 v[226:227], v[218:219], v[92:93], v[226:227]
	v_add_f32_e32 v118, v220, v221
	v_add_f32_e32 v119, v222, v223
	v_add_f32_e32 v120, v224, v225
	v_add_f32_e32 v121, v226, v227
	v_add_f32_dpp v118, v118, v118 quad_perm:[1,0,3,2] row_mask:0xf bank_mask:0xf
	v_add_f32_dpp v119, v119, v119 quad_perm:[1,0,3,2] row_mask:0xf bank_mask:0xf
	v_add_f32_dpp v120, v120, v120 quad_perm:[1,0,3,2] row_mask:0xf bank_mask:0xf
	v_add_f32_dpp v121, v121, v121 quad_perm:[1,0,3,2] row_mask:0xf bank_mask:0xf
	v_add_f32_dpp v118, v118, v118 quad_perm:[2,3,0,1] row_mask:0xf bank_mask:0xf
	v_add_f32_dpp v119, v119, v119 quad_perm:[2,3,0,1] row_mask:0xf bank_mask:0xf
	v_add_f32_dpp v120, v120, v120 quad_perm:[2,3,0,1] row_mask:0xf bank_mask:0xf
	v_add_f32_dpp v121, v121, v121 quad_perm:[2,3,0,1] row_mask:0xf bank_mask:0xf
	v_add_f32_dpp v118, v118, v118 row_half_mirror row_mask:0xf bank_mask:0xf
	v_add_f32_dpp v119, v119, v119 row_half_mirror row_mask:0xf bank_mask:0xf
	v_add_f32_dpp v120, v120, v120 row_half_mirror row_mask:0xf bank_mask:0xf
	v_add_f32_dpp v121, v121, v121 row_half_mirror row_mask:0xf bank_mask:0xf
	s_waitcnt vmcnt(18)
	v_cvt_pk_f32_fp8_e32 v[204:205], v180
	v_cvt_pk_f32_fp8_e32 v[206:207], v184
	v_pk_mul_f32 v[220:221], v[204:205], v[78:79]
	v_pk_mul_f32 v[222:223], v[206:207], v[78:79]
	v_cvt_pk_f32_fp8_sdwa v[208:209], v180 src0_sel:WORD_1
	v_cvt_pk_f32_fp8_sdwa v[210:211], v184 src0_sel:WORD_1
	v_pk_fma_f32 v[220:221], v[208:209], v[80:81], v[220:221]
	v_pk_fma_f32 v[222:223], v[210:211], v[80:81], v[222:223]
	v_cvt_pk_f32_fp8_e32 v[212:213], v181
	v_cvt_pk_f32_fp8_e32 v[214:215], v185
	v_pk_fma_f32 v[220:221], v[212:213], v[82:83], v[220:221]
	v_pk_fma_f32 v[222:223], v[214:215], v[82:83], v[222:223]
	v_cvt_pk_f32_fp8_sdwa v[216:217], v181 src0_sel:WORD_1
	v_cvt_pk_f32_fp8_sdwa v[218:219], v185 src0_sel:WORD_1
	v_pk_fma_f32 v[220:221], v[216:217], v[84:85], v[220:221]
	v_pk_fma_f32 v[222:223], v[218:219], v[84:85], v[222:223]
	v_cvt_pk_f32_fp8_e32 v[204:205], v182
	v_cvt_pk_f32_fp8_e32 v[206:207], v186
	v_pk_fma_f32 v[220:221], v[204:205], v[86:87], v[220:221]
	v_pk_fma_f32 v[222:223], v[206:207], v[86:87], v[222:223]
	v_cvt_pk_f32_fp8_sdwa v[208:209], v182 src0_sel:WORD_1
	v_cvt_pk_f32_fp8_sdwa v[210:211], v186 src0_sel:WORD_1
	v_pk_fma_f32 v[220:221], v[208:209], v[88:89], v[220:221]
	v_pk_fma_f32 v[222:223], v[210:211], v[88:89], v[222:223]
	v_cvt_pk_f32_fp8_e32 v[212:213], v183
	v_cvt_pk_f32_fp8_e32 v[214:215], v187
	v_pk_fma_f32 v[220:221], v[212:213], v[90:91], v[220:221]
	v_pk_fma_f32 v[222:223], v[214:215], v[90:91], v[222:223]
	v_cvt_pk_f32_fp8_sdwa v[216:217], v183 src0_sel:WORD_1
	v_cvt_pk_f32_fp8_sdwa v[218:219], v187 src0_sel:WORD_1
	v_pk_fma_f32 v[220:221], v[216:217], v[92:93], v[220:221]
	v_pk_fma_f32 v[222:223], v[218:219], v[92:93], v[222:223]
	s_waitcnt vmcnt(16)
; __device__ __forceinline__ void attn_phase(const Args& a, unsigned char* lds, int lane, int wave) {
;     ...
;                 d += __shfl_xor(d, 1); d += __shfl_xor(d, 2); d += __shfl_xor(d, 4); s[i] = d; }
;             const float mn = fmaxf(fmaxf(fmaxf(mx, fmaxf(s[0], s[1])), fmaxf(s[2], s[3])), fmaxf(fmaxf(s[4], s[5]), fmaxf(s[6], s[7])));
;             const float al = __builtin_amdgcn_exp2f(mx - mn);
;             float p[8];
; #pragma unroll
;             for (int i = 0; i < 8; ++i) p[i] = __builtin_amdgcn_exp2f(s[i] - mn);
;             l = l * al + ((p[0] + p[1]) + (p[2] + p[3])) + ((p[4] + p[5]) + (p[6] + p[7]));
; #pragma unroll
;             for (int d = 0; d < 16; ++d) o[d] *= al;
; #pragma unroll
;             for (int i = 0; i < 8; ++i) { float vf[16]; unpack16_fp8(vv[i], vf);
; #pragma unroll
;                 for (int d = 0; d < 16; ++d) o[d] += p[i] * vf[d]; }
	v_cvt_pk_f32_fp8_e32 v[204:205], v188
	v_cvt_pk_f32_fp8_e32 v[206:207], v192
	v_pk_mul_f32 v[224:225], v[204:205], v[78:79]
	v_pk_mul_f32 v[226:227], v[206:207], v[78:79]
	v_cvt_pk_f32_fp8_sdwa v[208:209], v188 src0_sel:WORD_1
	v_cvt_pk_f32_fp8_sdwa v[210:211], v192 src0_sel:WORD_1
	v_pk_fma_f32 v[224:225], v[208:209], v[80:81], v[224:225]
	v_pk_fma_f32 v[226:227], v[210:211], v[80:81], v[226:227]
	v_cvt_pk_f32_fp8_e32 v[212:213], v189
	v_cvt_pk_f32_fp8_e32 v[214:215], v193
	v_pk_fma_f32 v[224:225], v[212:213], v[82:83], v[224:225]
	v_pk_fma_f32 v[226:227], v[214:215], v[82:83], v[226:227]
	v_cvt_pk_f32_fp8_sdwa v[216:217], v189 src0_sel:WORD_1
	v_cvt_pk_f32_fp8_sdwa v[218:219], v193 src0_sel:WORD_1
	v_pk_fma_f32 v[224:225], v[216:217], v[84:85], v[224:225]
	v_pk_fma_f32 v[226:227], v[218:219], v[84:85], v[226:227]
	v_cvt_pk_f32_fp8_e32 v[204:205], v190
	v_cvt_pk_f32_fp8_e32 v[206:207], v194
	v_pk_fma_f32 v[224:225], v[204:205], v[86:87], v[224:225]
	v_pk_fma_f32 v[226:227], v[206:207], v[86:87], v[226:227]
	v_cvt_pk_f32_fp8_sdwa v[208:209], v190 src0_sel:WORD_1
	v_cvt_pk_f32_fp8_sdwa v[210:211], v194 src0_sel:WORD_1
	v_pk_fma_f32 v[224:225], v[208:209], v[88:89], v[224:225]
	v_pk_fma_f32 v[226:227], v[210:211], v[88:89], v[226:227]
	v_cvt_pk_f32_fp8_e32 v[212:213], v191
	v_cvt_pk_f32_fp8_e32 v[214:215], v195
	v_pk_fma_f32 v[224:225], v[212:213], v[90:91], v[224:225]
	v_pk_fma_f32 v[226:227], v[214:215], v[90:91], v[226:227]
	v_cvt_pk_f32_fp8_sdwa v[216:217], v191 src0_sel:WORD_1
	v_cvt_pk_f32_fp8_sdwa v[218:219], v195 src0_sel:WORD_1
	v_pk_fma_f32 v[224:225], v[216:217], v[92:93], v[224:225]
	v_pk_fma_f32 v[226:227], v[218:219], v[92:93], v[226:227]
	v_add_f32_e32 v122, v220, v221
	v_add_f32_e32 v123, v222, v223
	v_add_f32_e32 v124, v224, v225
	v_add_f32_e32 v125, v226, v227
	v_add_f32_dpp v122, v122, v122 quad_perm:[1,0,3,2] row_mask:0xf bank_mask:0xf
	v_add_f32_dpp v123, v123, v123 quad_perm:[1,0,3,2] row_mask:0xf bank_mask:0xf
	v_add_f32_dpp v124, v124, v124 quad_perm:[1,0,3,2] row_mask:0xf bank_mask:0xf
	v_add_f32_dpp v125, v125, v125 quad_perm:[1,0,3,2] row_mask:0xf bank_mask:0xf
	v_add_f32_dpp v122, v122, v122 quad_perm:[2,3,0,1] row_mask:0xf bank_mask:0xf
	v_add_f32_dpp v123, v123, v123 quad_perm:[2,3,0,1] row_mask:0xf bank_mask:0xf
	v_add_f32_dpp v124, v124, v124 quad_perm:[2,3,0,1] row_mask:0xf bank_mask:0xf
	v_add_f32_dpp v125, v125, v125 quad_perm:[2,3,0,1] row_mask:0xf bank_mask:0xf
	v_add_f32_dpp v122, v122, v122 row_half_mirror row_mask:0xf bank_mask:0xf
	v_add_f32_dpp v123, v123, v123 row_half_mirror row_mask:0xf bank_mask:0xf
	v_add_f32_dpp v124, v124, v124 row_half_mirror row_mask:0xf bank_mask:0xf
	v_add_f32_dpp v125, v125, v125 row_half_mirror row_mask:0xf bank_mask:0xf
	v_max3_f32 v228, v110, v111, v112
	v_max3_f32 v229, v113, v114, v115
	v_max3_f32 v230, v116, v117, v118
	v_max3_f32 v231, v119, v120, v121
	v_max3_f32 v232, v122, v123, v124
	v_max3_f32 v233, v125, v109, v228
	v_max3_f32 v234, v229, v230, v231
	v_max3_f32 v235, v232, v233, v234
	v_sub_f32_e32 v236, v109, v235
	v_sub_f32_e32 v110, v110, v235
	v_sub_f32_e32 v111, v111, v235
	v_sub_f32_e32 v112, v112, v235
	v_sub_f32_e32 v113, v113, v235
	v_sub_f32_e32 v114, v114, v235
	v_sub_f32_e32 v115, v115, v235
	v_sub_f32_e32 v116, v116, v235
	v_sub_f32_e32 v117, v117, v235
	v_sub_f32_e32 v118, v118, v235
	v_sub_f32_e32 v119, v119, v235
	v_sub_f32_e32 v120, v120, v235
	v_sub_f32_e32 v121, v121, v235
	v_sub_f32_e32 v122, v122, v235
	v_sub_f32_e32 v123, v123, v235
	v_sub_f32_e32 v124, v124, v235
	v_sub_f32_e32 v125, v125, v235
	v_exp_f32_e32 v244, v236
	v_exp_f32_e32 v110, v110
	v_exp_f32_e32 v111, v111
	v_exp_f32_e32 v112, v112
	v_exp_f32_e32 v113, v113
	v_exp_f32_e32 v114, v114
	v_exp_f32_e32 v115, v115
	v_exp_f32_e32 v116, v116
	v_exp_f32_e32 v117, v117
	v_exp_f32_e32 v118, v118
	v_exp_f32_e32 v119, v119
	v_exp_f32_e32 v120, v120
	v_exp_f32_e32 v121, v121
	v_exp_f32_e32 v122, v122
	v_exp_f32_e32 v123, v123
	v_exp_f32_e32 v124, v124
	v_exp_f32_e32 v125, v125
	v_mov_b32_e32 v109, v235
	v_pk_mul_f32 v[62:63], v[62:63], v[244:245] op_sel_hi:[1,0]
	v_pk_mul_f32 v[64:65], v[64:65], v[244:245] op_sel_hi:[1,0]
	v_pk_mul_f32 v[66:67], v[66:67], v[244:245] op_sel_hi:[1,0]
	v_pk_mul_f32 v[68:69], v[68:69], v[244:245] op_sel_hi:[1,0]
	v_pk_mul_f32 v[70:71], v[70:71], v[244:245] op_sel_hi:[1,0]
	v_pk_mul_f32 v[72:73], v[72:73], v[244:245] op_sel_hi:[1,0]
	v_pk_mul_f32 v[74:75], v[74:75], v[244:245] op_sel_hi:[1,0]
	v_pk_mul_f32 v[76:77], v[76:77], v[244:245] op_sel_hi:[1,0]
	v_add_f32_e32 v228, v110, v111
	v_add_f32_e32 v229, v112, v113
	v_add_f32_e32 v230, v114, v115
	v_add_f32_e32 v231, v116, v117
	v_add_f32_e32 v232, v118, v119
	v_add_f32_e32 v233, v120, v121
	v_add_f32_e32 v234, v122, v123
	v_add_f32_e32 v235, v124, v125
	v_add_f32_e32 v228, v228, v229
	v_add_f32_e32 v230, v230, v231
	v_add_f32_e32 v232, v232, v233
	v_add_f32_e32 v234, v234, v235
	v_add_f32_e32 v228, v228, v230
	v_add_f32_e32 v232, v232, v234
	v_add_f32_e32 v228, v228, v232
	v_fma_f32 v108, v108, v244, v228
	s_waitcnt vmcnt(15)
	v_cvt_pk_f32_fp8_e32 v[204:205], v0
	v_cvt_pk_f32_fp8_sdwa v[206:207], v0 src0_sel:WORD_1
	v_pk_fma_f32 v[62:63], v[204:205], v[110:111], v[62:63] op_sel_hi:[1,0,1]
	v_pk_fma_f32 v[64:65], v[206:207], v[110:111], v[64:65] op_sel_hi:[1,0,1]
	v_cvt_pk_f32_fp8_e32 v[208:209], v1
	v_cvt_pk_f32_fp8_sdwa v[210:211], v1 src0_sel:WORD_1
	v_pk_fma_f32 v[66:67], v[208:209], v[110:111], v[66:67] op_sel_hi:[1,0,1]
	v_pk_fma_f32 v[68:69], v[210:211], v[110:111], v[68:69] op_sel_hi:[1,0,1]
	v_cvt_pk_f32_fp8_e32 v[212:213], v2
	v_cvt_pk_f32_fp8_sdwa v[214:215], v2 src0_sel:WORD_1
	v_pk_fma_f32 v[70:71], v[212:213], v[110:111], v[70:71] op_sel_hi:[1,0,1]
	v_pk_fma_f32 v[72:73], v[214:215], v[110:111], v[72:73] op_sel_hi:[1,0,1]
	v_cvt_pk_f32_fp8_e32 v[216:217], v3
	v_cvt_pk_f32_fp8_sdwa v[218:219], v3 src0_sel:WORD_1
	v_pk_fma_f32 v[74:75], v[216:217], v[110:111], v[74:75] op_sel_hi:[1,0,1]
	v_pk_fma_f32 v[76:77], v[218:219], v[110:111], v[76:77] op_sel_hi:[1,0,1]
	s_waitcnt vmcnt(14)
; __device__ __forceinline__ void attn_phase(const Args& a, unsigned char* lds, int lane, int wave) {
;     ...
;             for (int i = 0; i < 8; ++i) { float vf[16]; unpack16_fp8(vv[i], vf);
; #pragma unroll
;                 for (int d = 0; d < 16; ++d) o[d] += p[i] * vf[d]; }
	v_cvt_pk_f32_fp8_e32 v[204:205], v4
	v_cvt_pk_f32_fp8_sdwa v[206:207], v4 src0_sel:WORD_1
	v_pk_fma_f32 v[62:63], v[204:205], v[110:111], v[62:63] op_sel:[0,1,0] op_sel_hi:[1,1,1]
	v_pk_fma_f32 v[64:65], v[206:207], v[110:111], v[64:65] op_sel:[0,1,0] op_sel_hi:[1,1,1]
	v_cvt_pk_f32_fp8_e32 v[208:209], v5
	v_cvt_pk_f32_fp8_sdwa v[210:211], v5 src0_sel:WORD_1
	v_pk_fma_f32 v[66:67], v[208:209], v[110:111], v[66:67] op_sel:[0,1,0] op_sel_hi:[1,1,1]
	v_pk_fma_f32 v[68:69], v[210:211], v[110:111], v[68:69] op_sel:[0,1,0] op_sel_hi:[1,1,1]
	v_cvt_pk_f32_fp8_e32 v[212:213], v6
	v_cvt_pk_f32_fp8_sdwa v[214:215], v6 src0_sel:WORD_1
	v_pk_fma_f32 v[70:71], v[212:213], v[110:111], v[70:71] op_sel:[0,1,0] op_sel_hi:[1,1,1]
	v_pk_fma_f32 v[72:73], v[214:215], v[110:111], v[72:73] op_sel:[0,1,0] op_sel_hi:[1,1,1]
	v_cvt_pk_f32_fp8_e32 v[216:217], v7
	v_cvt_pk_f32_fp8_sdwa v[218:219], v7 src0_sel:WORD_1
	v_pk_fma_f32 v[74:75], v[216:217], v[110:111], v[74:75] op_sel:[0,1,0] op_sel_hi:[1,1,1]
	v_pk_fma_f32 v[76:77], v[218:219], v[110:111], v[76:77] op_sel:[0,1,0] op_sel_hi:[1,1,1]
	s_waitcnt vmcnt(13)
	v_cvt_pk_f32_fp8_e32 v[204:205], v8
	v_cvt_pk_f32_fp8_sdwa v[206:207], v8 src0_sel:WORD_1
	v_pk_fma_f32 v[62:63], v[204:205], v[112:113], v[62:63] op_sel_hi:[1,0,1]
	v_pk_fma_f32 v[64:65], v[206:207], v[112:113], v[64:65] op_sel_hi:[1,0,1]
	v_cvt_pk_f32_fp8_e32 v[208:209], v9
	v_cvt_pk_f32_fp8_sdwa v[210:211], v9 src0_sel:WORD_1
	v_pk_fma_f32 v[66:67], v[208:209], v[112:113], v[66:67] op_sel_hi:[1,0,1]
	v_pk_fma_f32 v[68:69], v[210:211], v[112:113], v[68:69] op_sel_hi:[1,0,1]
	v_cvt_pk_f32_fp8_e32 v[212:213], v10
	v_cvt_pk_f32_fp8_sdwa v[214:215], v10 src0_sel:WORD_1
	v_pk_fma_f32 v[70:71], v[212:213], v[112:113], v[70:71] op_sel_hi:[1,0,1]
	v_pk_fma_f32 v[72:73], v[214:215], v[112:113], v[72:73] op_sel_hi:[1,0,1]
	v_cvt_pk_f32_fp8_e32 v[216:217], v11
	v_cvt_pk_f32_fp8_sdwa v[218:219], v11 src0_sel:WORD_1
	v_pk_fma_f32 v[74:75], v[216:217], v[112:113], v[74:75] op_sel_hi:[1,0,1]
	v_pk_fma_f32 v[76:77], v[218:219], v[112:113], v[76:77] op_sel_hi:[1,0,1]
	s_waitcnt vmcnt(12)
	v_cvt_pk_f32_fp8_e32 v[204:205], v12
	v_cvt_pk_f32_fp8_sdwa v[206:207], v12 src0_sel:WORD_1
	v_pk_fma_f32 v[62:63], v[204:205], v[112:113], v[62:63] op_sel:[0,1,0] op_sel_hi:[1,1,1]
	v_pk_fma_f32 v[64:65], v[206:207], v[112:113], v[64:65] op_sel:[0,1,0] op_sel_hi:[1,1,1]
	v_cvt_pk_f32_fp8_e32 v[208:209], v13
	v_cvt_pk_f32_fp8_sdwa v[210:211], v13 src0_sel:WORD_1
	v_pk_fma_f32 v[66:67], v[208:209], v[112:113], v[66:67] op_sel:[0,1,0] op_sel_hi:[1,1,1]
	v_pk_fma_f32 v[68:69], v[210:211], v[112:113], v[68:69] op_sel:[0,1,0] op_sel_hi:[1,1,1]
	v_cvt_pk_f32_fp8_e32 v[212:213], v14
	v_cvt_pk_f32_fp8_sdwa v[214:215], v14 src0_sel:WORD_1
	v_pk_fma_f32 v[70:71], v[212:213], v[112:113], v[70:71] op_sel:[0,1,0] op_sel_hi:[1,1,1]
	v_pk_fma_f32 v[72:73], v[214:215], v[112:113], v[72:73] op_sel:[0,1,0] op_sel_hi:[1,1,1]
	v_cvt_pk_f32_fp8_e32 v[216:217], v15
	v_cvt_pk_f32_fp8_sdwa v[218:219], v15 src0_sel:WORD_1
	v_pk_fma_f32 v[74:75], v[216:217], v[112:113], v[74:75] op_sel:[0,1,0] op_sel_hi:[1,1,1]
	v_pk_fma_f32 v[76:77], v[218:219], v[112:113], v[76:77] op_sel:[0,1,0] op_sel_hi:[1,1,1]
	s_waitcnt vmcnt(11)
	v_cvt_pk_f32_fp8_e32 v[204:205], v16
	v_cvt_pk_f32_fp8_sdwa v[206:207], v16 src0_sel:WORD_1
	v_pk_fma_f32 v[62:63], v[204:205], v[114:115], v[62:63] op_sel_hi:[1,0,1]
	v_pk_fma_f32 v[64:65], v[206:207], v[114:115], v[64:65] op_sel_hi:[1,0,1]
	v_cvt_pk_f32_fp8_e32 v[208:209], v17
	v_cvt_pk_f32_fp8_sdwa v[210:211], v17 src0_sel:WORD_1
	v_pk_fma_f32 v[66:67], v[208:209], v[114:115], v[66:67] op_sel_hi:[1,0,1]
	v_pk_fma_f32 v[68:69], v[210:211], v[114:115], v[68:69] op_sel_hi:[1,0,1]
	v_cvt_pk_f32_fp8_e32 v[212:213], v18
	v_cvt_pk_f32_fp8_sdwa v[214:215], v18 src0_sel:WORD_1
	v_pk_fma_f32 v[70:71], v[212:213], v[114:115], v[70:71] op_sel_hi:[1,0,1]
	v_pk_fma_f32 v[72:73], v[214:215], v[114:115], v[72:73] op_sel_hi:[1,0,1]
	v_cvt_pk_f32_fp8_e32 v[216:217], v19
	v_cvt_pk_f32_fp8_sdwa v[218:219], v19 src0_sel:WORD_1
	v_pk_fma_f32 v[74:75], v[216:217], v[114:115], v[74:75] op_sel_hi:[1,0,1]
	v_pk_fma_f32 v[76:77], v[218:219], v[114:115], v[76:77] op_sel_hi:[1,0,1]
	s_waitcnt vmcnt(10)
	v_cvt_pk_f32_fp8_e32 v[204:205], v20
	v_cvt_pk_f32_fp8_sdwa v[206:207], v20 src0_sel:WORD_1
	v_pk_fma_f32 v[62:63], v[204:205], v[114:115], v[62:63] op_sel:[0,1,0] op_sel_hi:[1,1,1]
	v_pk_fma_f32 v[64:65], v[206:207], v[114:115], v[64:65] op_sel:[0,1,0] op_sel_hi:[1,1,1]
	v_cvt_pk_f32_fp8_e32 v[208:209], v21
	v_cvt_pk_f32_fp8_sdwa v[210:211], v21 src0_sel:WORD_1
	v_pk_fma_f32 v[66:67], v[208:209], v[114:115], v[66:67] op_sel:[0,1,0] op_sel_hi:[1,1,1]
	v_pk_fma_f32 v[68:69], v[210:211], v[114:115], v[68:69] op_sel:[0,1,0] op_sel_hi:[1,1,1]
	v_cvt_pk_f32_fp8_e32 v[212:213], v22
	v_cvt_pk_f32_fp8_sdwa v[214:215], v22 src0_sel:WORD_1
	v_pk_fma_f32 v[70:71], v[212:213], v[114:115], v[70:71] op_sel:[0,1,0] op_sel_hi:[1,1,1]
	v_pk_fma_f32 v[72:73], v[214:215], v[114:115], v[72:73] op_sel:[0,1,0] op_sel_hi:[1,1,1]
	v_cvt_pk_f32_fp8_e32 v[216:217], v23
	v_cvt_pk_f32_fp8_sdwa v[218:219], v23 src0_sel:WORD_1
	v_pk_fma_f32 v[74:75], v[216:217], v[114:115], v[74:75] op_sel:[0,1,0] op_sel_hi:[1,1,1]
	v_pk_fma_f32 v[76:77], v[218:219], v[114:115], v[76:77] op_sel:[0,1,0] op_sel_hi:[1,1,1]
	s_waitcnt vmcnt(9)
; __device__ __forceinline__ void attn_phase(const Args& a, unsigned char* lds, int lane, int wave) {
;     ...
;             for (int i = 0; i < 8; ++i) { float vf[16]; unpack16_fp8(vv[i], vf);
; #pragma unroll
;                 for (int d = 0; d < 16; ++d) o[d] += p[i] * vf[d]; }
	v_cvt_pk_f32_fp8_e32 v[204:205], v24
	v_cvt_pk_f32_fp8_sdwa v[206:207], v24 src0_sel:WORD_1
	v_pk_fma_f32 v[62:63], v[204:205], v[116:117], v[62:63] op_sel_hi:[1,0,1]
	v_pk_fma_f32 v[64:65], v[206:207], v[116:117], v[64:65] op_sel_hi:[1,0,1]
	v_cvt_pk_f32_fp8_e32 v[208:209], v25
	v_cvt_pk_f32_fp8_sdwa v[210:211], v25 src0_sel:WORD_1
	v_pk_fma_f32 v[66:67], v[208:209], v[116:117], v[66:67] op_sel_hi:[1,0,1]
	v_pk_fma_f32 v[68:69], v[210:211], v[116:117], v[68:69] op_sel_hi:[1,0,1]
	v_cvt_pk_f32_fp8_e32 v[212:213], v26
	v_cvt_pk_f32_fp8_sdwa v[214:215], v26 src0_sel:WORD_1
	v_pk_fma_f32 v[70:71], v[212:213], v[116:117], v[70:71] op_sel_hi:[1,0,1]
	v_pk_fma_f32 v[72:73], v[214:215], v[116:117], v[72:73] op_sel_hi:[1,0,1]
	v_cvt_pk_f32_fp8_e32 v[216:217], v27
	v_cvt_pk_f32_fp8_sdwa v[218:219], v27 src0_sel:WORD_1
	v_pk_fma_f32 v[74:75], v[216:217], v[116:117], v[74:75] op_sel_hi:[1,0,1]
	v_pk_fma_f32 v[76:77], v[218:219], v[116:117], v[76:77] op_sel_hi:[1,0,1]
	s_waitcnt vmcnt(8)
	v_cvt_pk_f32_fp8_e32 v[204:205], v28
	v_cvt_pk_f32_fp8_sdwa v[206:207], v28 src0_sel:WORD_1
	v_pk_fma_f32 v[62:63], v[204:205], v[116:117], v[62:63] op_sel:[0,1,0] op_sel_hi:[1,1,1]
	v_pk_fma_f32 v[64:65], v[206:207], v[116:117], v[64:65] op_sel:[0,1,0] op_sel_hi:[1,1,1]
	v_cvt_pk_f32_fp8_e32 v[208:209], v29
	v_cvt_pk_f32_fp8_sdwa v[210:211], v29 src0_sel:WORD_1
	v_pk_fma_f32 v[66:67], v[208:209], v[116:117], v[66:67] op_sel:[0,1,0] op_sel_hi:[1,1,1]
	v_pk_fma_f32 v[68:69], v[210:211], v[116:117], v[68:69] op_sel:[0,1,0] op_sel_hi:[1,1,1]
	v_cvt_pk_f32_fp8_e32 v[212:213], v30
	v_cvt_pk_f32_fp8_sdwa v[214:215], v30 src0_sel:WORD_1
	v_pk_fma_f32 v[70:71], v[212:213], v[116:117], v[70:71] op_sel:[0,1,0] op_sel_hi:[1,1,1]
	v_pk_fma_f32 v[72:73], v[214:215], v[116:117], v[72:73] op_sel:[0,1,0] op_sel_hi:[1,1,1]
	v_cvt_pk_f32_fp8_e32 v[216:217], v31
	v_cvt_pk_f32_fp8_sdwa v[218:219], v31 src0_sel:WORD_1
	v_pk_fma_f32 v[74:75], v[216:217], v[116:117], v[74:75] op_sel:[0,1,0] op_sel_hi:[1,1,1]
	v_pk_fma_f32 v[76:77], v[218:219], v[116:117], v[76:77] op_sel:[0,1,0] op_sel_hi:[1,1,1]
	s_waitcnt vmcnt(7)
	v_cvt_pk_f32_fp8_e32 v[204:205], v32
	v_cvt_pk_f32_fp8_sdwa v[206:207], v32 src0_sel:WORD_1
	v_pk_fma_f32 v[62:63], v[204:205], v[118:119], v[62:63] op_sel_hi:[1,0,1]
	v_pk_fma_f32 v[64:65], v[206:207], v[118:119], v[64:65] op_sel_hi:[1,0,1]
	v_cvt_pk_f32_fp8_e32 v[208:209], v33
	v_cvt_pk_f32_fp8_sdwa v[210:211], v33 src0_sel:WORD_1
	v_pk_fma_f32 v[66:67], v[208:209], v[118:119], v[66:67] op_sel_hi:[1,0,1]
	v_pk_fma_f32 v[68:69], v[210:211], v[118:119], v[68:69] op_sel_hi:[1,0,1]
	v_cvt_pk_f32_fp8_e32 v[212:213], v34
	v_cvt_pk_f32_fp8_sdwa v[214:215], v34 src0_sel:WORD_1
	v_pk_fma_f32 v[70:71], v[212:213], v[118:119], v[70:71] op_sel_hi:[1,0,1]
	v_pk_fma_f32 v[72:73], v[214:215], v[118:119], v[72:73] op_sel_hi:[1,0,1]
	v_cvt_pk_f32_fp8_e32 v[216:217], v35
	v_cvt_pk_f32_fp8_sdwa v[218:219], v35 src0_sel:WORD_1
	v_pk_fma_f32 v[74:75], v[216:217], v[118:119], v[74:75] op_sel_hi:[1,0,1]
	v_pk_fma_f32 v[76:77], v[218:219], v[118:119], v[76:77] op_sel_hi:[1,0,1]
	s_waitcnt vmcnt(6)
	v_cvt_pk_f32_fp8_e32 v[204:205], v36
	v_cvt_pk_f32_fp8_sdwa v[206:207], v36 src0_sel:WORD_1
	v_pk_fma_f32 v[62:63], v[204:205], v[118:119], v[62:63] op_sel:[0,1,0] op_sel_hi:[1,1,1]
	v_pk_fma_f32 v[64:65], v[206:207], v[118:119], v[64:65] op_sel:[0,1,0] op_sel_hi:[1,1,1]
	v_cvt_pk_f32_fp8_e32 v[208:209], v37
	v_cvt_pk_f32_fp8_sdwa v[210:211], v37 src0_sel:WORD_1
	v_pk_fma_f32 v[66:67], v[208:209], v[118:119], v[66:67] op_sel:[0,1,0] op_sel_hi:[1,1,1]
	v_pk_fma_f32 v[68:69], v[210:211], v[118:119], v[68:69] op_sel:[0,1,0] op_sel_hi:[1,1,1]
	v_cvt_pk_f32_fp8_e32 v[212:213], v38
	v_cvt_pk_f32_fp8_sdwa v[214:215], v38 src0_sel:WORD_1
	v_pk_fma_f32 v[70:71], v[212:213], v[118:119], v[70:71] op_sel:[0,1,0] op_sel_hi:[1,1,1]
	v_pk_fma_f32 v[72:73], v[214:215], v[118:119], v[72:73] op_sel:[0,1,0] op_sel_hi:[1,1,1]
	v_cvt_pk_f32_fp8_e32 v[216:217], v39
	v_cvt_pk_f32_fp8_sdwa v[218:219], v39 src0_sel:WORD_1
	v_pk_fma_f32 v[74:75], v[216:217], v[118:119], v[74:75] op_sel:[0,1,0] op_sel_hi:[1,1,1]
	v_pk_fma_f32 v[76:77], v[218:219], v[118:119], v[76:77] op_sel:[0,1,0] op_sel_hi:[1,1,1]
	s_waitcnt vmcnt(5)
	v_cvt_pk_f32_fp8_e32 v[204:205], v40
	v_cvt_pk_f32_fp8_sdwa v[206:207], v40 src0_sel:WORD_1
	v_pk_fma_f32 v[62:63], v[204:205], v[120:121], v[62:63] op_sel_hi:[1,0,1]
	v_pk_fma_f32 v[64:65], v[206:207], v[120:121], v[64:65] op_sel_hi:[1,0,1]
	v_cvt_pk_f32_fp8_e32 v[208:209], v41
	v_cvt_pk_f32_fp8_sdwa v[210:211], v41 src0_sel:WORD_1
	v_pk_fma_f32 v[66:67], v[208:209], v[120:121], v[66:67] op_sel_hi:[1,0,1]
	v_pk_fma_f32 v[68:69], v[210:211], v[120:121], v[68:69] op_sel_hi:[1,0,1]
	v_cvt_pk_f32_fp8_e32 v[212:213], v42
	v_cvt_pk_f32_fp8_sdwa v[214:215], v42 src0_sel:WORD_1
	v_pk_fma_f32 v[70:71], v[212:213], v[120:121], v[70:71] op_sel_hi:[1,0,1]
	v_pk_fma_f32 v[72:73], v[214:215], v[120:121], v[72:73] op_sel_hi:[1,0,1]
	v_cvt_pk_f32_fp8_e32 v[216:217], v43
	v_cvt_pk_f32_fp8_sdwa v[218:219], v43 src0_sel:WORD_1
	v_pk_fma_f32 v[74:75], v[216:217], v[120:121], v[74:75] op_sel_hi:[1,0,1]
	v_pk_fma_f32 v[76:77], v[218:219], v[120:121], v[76:77] op_sel_hi:[1,0,1]
	s_waitcnt vmcnt(4)
; __device__ __forceinline__ u32x4 pack8(const float* v) { u32x4 w; w.x = pk2(v[0], v[1]); w.y = pk2(v[2], v[3]); w.z = pk2(v[4], v[5]); w.w = pk2(v[6], v[7]); return w; }
; __device__ __forceinline__ void attn_phase(const Args& a, unsigned char* lds, int lane, int wave) {
;     ...
;     for (int t = gw; t < TT; t += NGW) {
;     ...
;             for (int i = 0; i < 8; ++i) { float vf[16]; unpack16_fp8(vv[i], vf);
; #pragma unroll
;                 for (int d = 0; d < 16; ++d) o[d] += p[i] * vf[d]; }
;             mx = mn;
;         }
;         const float il = 1.f / l;
; #pragma unroll
;         for (int d = 0; d < 16; ++d) o[d] *= il;
;         *(u32x4*)qp = pack8(o); *(u32x4*)(qp + 8) = pack8(o + 8);
	v_cvt_pk_f32_fp8_e32 v[204:205], v44
	v_cvt_pk_f32_fp8_sdwa v[206:207], v44 src0_sel:WORD_1
	v_pk_fma_f32 v[62:63], v[204:205], v[120:121], v[62:63] op_sel:[0,1,0] op_sel_hi:[1,1,1]
	v_pk_fma_f32 v[64:65], v[206:207], v[120:121], v[64:65] op_sel:[0,1,0] op_sel_hi:[1,1,1]
	v_cvt_pk_f32_fp8_e32 v[208:209], v45
	v_cvt_pk_f32_fp8_sdwa v[210:211], v45 src0_sel:WORD_1
	v_pk_fma_f32 v[66:67], v[208:209], v[120:121], v[66:67] op_sel:[0,1,0] op_sel_hi:[1,1,1]
	v_pk_fma_f32 v[68:69], v[210:211], v[120:121], v[68:69] op_sel:[0,1,0] op_sel_hi:[1,1,1]
	v_cvt_pk_f32_fp8_e32 v[212:213], v46
	v_cvt_pk_f32_fp8_sdwa v[214:215], v46 src0_sel:WORD_1
	v_pk_fma_f32 v[70:71], v[212:213], v[120:121], v[70:71] op_sel:[0,1,0] op_sel_hi:[1,1,1]
	v_pk_fma_f32 v[72:73], v[214:215], v[120:121], v[72:73] op_sel:[0,1,0] op_sel_hi:[1,1,1]
	v_cvt_pk_f32_fp8_e32 v[216:217], v47
	v_cvt_pk_f32_fp8_sdwa v[218:219], v47 src0_sel:WORD_1
	v_pk_fma_f32 v[74:75], v[216:217], v[120:121], v[74:75] op_sel:[0,1,0] op_sel_hi:[1,1,1]
	v_pk_fma_f32 v[76:77], v[218:219], v[120:121], v[76:77] op_sel:[0,1,0] op_sel_hi:[1,1,1]
	s_waitcnt vmcnt(3)
	v_cvt_pk_f32_fp8_e32 v[204:205], v48
	v_cvt_pk_f32_fp8_sdwa v[206:207], v48 src0_sel:WORD_1
	v_pk_fma_f32 v[62:63], v[204:205], v[122:123], v[62:63] op_sel_hi:[1,0,1]
	v_pk_fma_f32 v[64:65], v[206:207], v[122:123], v[64:65] op_sel_hi:[1,0,1]
	v_cvt_pk_f32_fp8_e32 v[208:209], v49
	v_cvt_pk_f32_fp8_sdwa v[210:211], v49 src0_sel:WORD_1
	v_pk_fma_f32 v[66:67], v[208:209], v[122:123], v[66:67] op_sel_hi:[1,0,1]
	v_pk_fma_f32 v[68:69], v[210:211], v[122:123], v[68:69] op_sel_hi:[1,0,1]
	v_cvt_pk_f32_fp8_e32 v[212:213], v50
	v_cvt_pk_f32_fp8_sdwa v[214:215], v50 src0_sel:WORD_1
	v_pk_fma_f32 v[70:71], v[212:213], v[122:123], v[70:71] op_sel_hi:[1,0,1]
	v_pk_fma_f32 v[72:73], v[214:215], v[122:123], v[72:73] op_sel_hi:[1,0,1]
	v_cvt_pk_f32_fp8_e32 v[216:217], v51
	v_cvt_pk_f32_fp8_sdwa v[218:219], v51 src0_sel:WORD_1
	v_pk_fma_f32 v[74:75], v[216:217], v[122:123], v[74:75] op_sel_hi:[1,0,1]
	v_pk_fma_f32 v[76:77], v[218:219], v[122:123], v[76:77] op_sel_hi:[1,0,1]
	s_waitcnt vmcnt(2)
	v_cvt_pk_f32_fp8_e32 v[204:205], v52
	v_cvt_pk_f32_fp8_sdwa v[206:207], v52 src0_sel:WORD_1
	v_pk_fma_f32 v[62:63], v[204:205], v[122:123], v[62:63] op_sel:[0,1,0] op_sel_hi:[1,1,1]
	v_pk_fma_f32 v[64:65], v[206:207], v[122:123], v[64:65] op_sel:[0,1,0] op_sel_hi:[1,1,1]
	v_cvt_pk_f32_fp8_e32 v[208:209], v53
	v_cvt_pk_f32_fp8_sdwa v[210:211], v53 src0_sel:WORD_1
	v_pk_fma_f32 v[66:67], v[208:209], v[122:123], v[66:67] op_sel:[0,1,0] op_sel_hi:[1,1,1]
	v_pk_fma_f32 v[68:69], v[210:211], v[122:123], v[68:69] op_sel:[0,1,0] op_sel_hi:[1,1,1]
	v_cvt_pk_f32_fp8_e32 v[212:213], v54
	v_cvt_pk_f32_fp8_sdwa v[214:215], v54 src0_sel:WORD_1
	v_pk_fma_f32 v[70:71], v[212:213], v[122:123], v[70:71] op_sel:[0,1,0] op_sel_hi:[1,1,1]
	v_pk_fma_f32 v[72:73], v[214:215], v[122:123], v[72:73] op_sel:[0,1,0] op_sel_hi:[1,1,1]
	v_cvt_pk_f32_fp8_e32 v[216:217], v55
	v_cvt_pk_f32_fp8_sdwa v[218:219], v55 src0_sel:WORD_1
	v_pk_fma_f32 v[74:75], v[216:217], v[122:123], v[74:75] op_sel:[0,1,0] op_sel_hi:[1,1,1]
	v_pk_fma_f32 v[76:77], v[218:219], v[122:123], v[76:77] op_sel:[0,1,0] op_sel_hi:[1,1,1]
	s_waitcnt vmcnt(1)
	v_cvt_pk_f32_fp8_e32 v[204:205], v196
	v_cvt_pk_f32_fp8_sdwa v[206:207], v196 src0_sel:WORD_1
	v_pk_fma_f32 v[62:63], v[204:205], v[124:125], v[62:63] op_sel_hi:[1,0,1]
	v_pk_fma_f32 v[64:65], v[206:207], v[124:125], v[64:65] op_sel_hi:[1,0,1]
	v_cvt_pk_f32_fp8_e32 v[208:209], v197
	v_cvt_pk_f32_fp8_sdwa v[210:211], v197 src0_sel:WORD_1
	v_pk_fma_f32 v[66:67], v[208:209], v[124:125], v[66:67] op_sel_hi:[1,0,1]
	v_pk_fma_f32 v[68:69], v[210:211], v[124:125], v[68:69] op_sel_hi:[1,0,1]
	v_cvt_pk_f32_fp8_e32 v[212:213], v198
	v_cvt_pk_f32_fp8_sdwa v[214:215], v198 src0_sel:WORD_1
	v_pk_fma_f32 v[70:71], v[212:213], v[124:125], v[70:71] op_sel_hi:[1,0,1]
	v_pk_fma_f32 v[72:73], v[214:215], v[124:125], v[72:73] op_sel_hi:[1,0,1]
	v_cvt_pk_f32_fp8_e32 v[216:217], v199
	v_cvt_pk_f32_fp8_sdwa v[218:219], v199 src0_sel:WORD_1
	v_pk_fma_f32 v[74:75], v[216:217], v[124:125], v[74:75] op_sel_hi:[1,0,1]
	v_pk_fma_f32 v[76:77], v[218:219], v[124:125], v[76:77] op_sel_hi:[1,0,1]
	s_waitcnt vmcnt(0)
	v_cvt_pk_f32_fp8_e32 v[204:205], v200
	v_cvt_pk_f32_fp8_sdwa v[206:207], v200 src0_sel:WORD_1
	v_pk_fma_f32 v[62:63], v[204:205], v[124:125], v[62:63] op_sel:[0,1,0] op_sel_hi:[1,1,1]
	v_pk_fma_f32 v[64:65], v[206:207], v[124:125], v[64:65] op_sel:[0,1,0] op_sel_hi:[1,1,1]
	v_cvt_pk_f32_fp8_e32 v[208:209], v201
	v_cvt_pk_f32_fp8_sdwa v[210:211], v201 src0_sel:WORD_1
	v_pk_fma_f32 v[66:67], v[208:209], v[124:125], v[66:67] op_sel:[0,1,0] op_sel_hi:[1,1,1]
	v_pk_fma_f32 v[68:69], v[210:211], v[124:125], v[68:69] op_sel:[0,1,0] op_sel_hi:[1,1,1]
	v_cvt_pk_f32_fp8_e32 v[212:213], v202
	v_cvt_pk_f32_fp8_sdwa v[214:215], v202 src0_sel:WORD_1
	v_pk_fma_f32 v[70:71], v[212:213], v[124:125], v[70:71] op_sel:[0,1,0] op_sel_hi:[1,1,1]
	v_pk_fma_f32 v[72:73], v[214:215], v[124:125], v[72:73] op_sel:[0,1,0] op_sel_hi:[1,1,1]
	v_cvt_pk_f32_fp8_e32 v[216:217], v203
	v_cvt_pk_f32_fp8_sdwa v[218:219], v203 src0_sel:WORD_1
	v_pk_fma_f32 v[74:75], v[216:217], v[124:125], v[74:75] op_sel:[0,1,0] op_sel_hi:[1,1,1]
	v_pk_fma_f32 v[76:77], v[218:219], v[124:125], v[76:77] op_sel:[0,1,0] op_sel_hi:[1,1,1]
	v_div_scale_f32 v0, s[0:1], v108, v108, 1.0
	v_rcp_f32_e32 v1, v0
	v_div_scale_f32 v2, vcc, 1.0, v108, 1.0
	s_add_i32 s2, s2, s28
	v_fma_f32 v3, -v0, v1, 1.0
	v_fmac_f32_e32 v1, v3, v1
	v_mul_f32_e32 v3, v2, v1
	v_fma_f32 v4, -v0, v3, v2
	v_fmac_f32_e32 v3, v4, v1
	v_fma_f32 v0, -v0, v3, v2
	v_div_fmas_f32 v0, v0, v1, v3
	v_div_fixup_f32 v0, v0, v108, 1.0
	v_pk_mul_f32 v[62:63], v[62:63], v[0:1] op_sel_hi:[1,0]
	v_pk_mul_f32 v[64:65], v[64:65], v[0:1] op_sel_hi:[1,0]
	v_pk_mul_f32 v[66:67], v[66:67], v[0:1] op_sel_hi:[1,0]
	v_pk_mul_f32 v[68:69], v[68:69], v[0:1] op_sel_hi:[1,0]
	v_pk_mul_f32 v[70:71], v[70:71], v[0:1] op_sel_hi:[1,0]
	v_pk_mul_f32 v[72:73], v[72:73], v[0:1] op_sel_hi:[1,0]
	v_pk_mul_f32 v[74:75], v[74:75], v[0:1] op_sel_hi:[1,0]
	v_pk_mul_f32 v[76:77], v[76:77], v[0:1] op_sel_hi:[1,0]
	v_cvt_pk_bf16_f32 v4, v62, v63
	v_cvt_pk_bf16_f32 v5, v64, v65
	v_cvt_pk_bf16_f32 v6, v66, v67
	v_cvt_pk_bf16_f32 v7, v68, v69
	v_cvt_pk_bf16_f32 v8, v70, v71
	v_cvt_pk_bf16_f32 v9, v72, v73
	v_cvt_pk_bf16_f32 v10, v74, v75
	v_cvt_pk_bf16_f32 v11, v76, v77
	global_store_dwordx4 v[60:61], v[4:7], off
	global_store_dwordx4 v[60:61], v[8:11], off offset:16
	s_cmpk_gt_i32 s2, 0x41ff
	s_cbranch_scc0 .Lat_q
